# E20 + out-proj residual epilogue (layers 0-2): both 128-column halves' residual loads of a row issued together instead of load-wait-store-load-wait (7 of 8 rows)
# baseline (speedup 1.0000x reference)
; DI u32 pack2(float a, float b) { f32v2 v = {a, b}; return __builtin_bit_cast(u32, __builtin_convertvector(v, bf16v2)); }
;   DI void operator()(const f32x4 (&acc)[2][2][4][2], const Unit& u, int wr, int wc, int fr, int fq) const {
;     ...
;     for (int ai = 0; ai < 2; ++ai)
; #pragma unroll
;       for (int m = 0; m < 4; ++m) {
;         const int row = row0 + ai * HALF + m * 16;
;         float* dst = out + (size_t)row * DM + col0;
;         const float* src = layer == 0 ? (row < PROWS ? xp + (size_t)row * DM + col0 : xs + (size_t)(row - PROWS) * DM + col0) : dst;
;         float ss = 0.f;
; #pragma unroll
;         for (int bj = 0; bj < 2; ++bj) {
;           const f32x4 x0 = *reinterpret_cast<const f32x4*>(src + bj * HALF), x1 = *reinterpret_cast<const f32x4*>(src + bj * HALF + 4);
;           const f32x4 n0 = x0 + acc[ai][bj][m][0], n1 = x1 + acc[ai][bj][m][1];
;           *reinterpret_cast<f32x4*>(dst + bj * HALF) = n0; *reinterpret_cast<f32x4*>(dst + bj * HALF + 4) = n1;
;           ss += n0[0] * n0[0] + n0[1] * n0[1] + n0[2] * n0[2] + n0[3] * n0[3] + n1[0] * n1[0] + n1[1] * n1[1] + n1[2] * n1[2] + n1[3] * n1[3];
;           if (xw) {
;             const f32x4 h0 = n0 * wv[bj][0], h1 = n1 * wv[bj][1];
;             u32x4 pk = {pack2(h0[0], h0[1]), pack2(h0[2], h0[3]), pack2(h1[0], h1[1]), pack2(h1[2], h1[3])};
;             *reinterpret_cast<u32x4*>(xw + (size_t)row * DM + col0 + bj * HALF) = pk;
;           }
;         }
;         ss += __shfl_xor(ss, 16); ss += __shfl_xor(ss, 32);
;         if (fq == 0) atomicAdd(rs + row, ss);
;       }
.LBB0_369:
	s_or_b64 exec, exec, s[22:23]
	v_or_b32_e32 v128, 16, v166
	s_waitcnt lgkmcnt(0)
	v_ashrrev_i32_e32 v129, 31, v128
	v_add_u32_e32 v152, 0xffffc010, v166
	v_lshlrev_b64 v[134:135], 13, v[128:129]
	v_lshlrev_b64 v[132:133], 13, v[152:153]
	v_lshl_add_u64 v[130:131], s[40:41], 0, v[134:135]
	v_lshl_add_u64 v[132:133], s[42:43], 0, v[132:133]
	v_cmp_gt_i32_e32 vcc, s55, v128
	v_lshlrev_b64 v[176:177], 12, v[128:129]
	v_lshl_add_u64 v[134:135], s[36:37], 0, v[134:135]
	v_cndmask_b32_e32 v131, v133, v131, vcc
	v_cndmask_b32_e32 v130, v132, v130, vcc
	v_lshl_add_u64 v[142:143], v[130:131], 0, v[164:165]
	global_load_dwordx4 v[130:133], v[142:143], off
	global_load_dwordx4 v[138:141], v[142:143], off offset:16
	global_load_dwordx4 v[178:181], v[142:143], off offset:512
	global_load_dwordx4 v[182:185], v[142:143], off offset:528
	v_lshl_add_u64 v[176:177], s[10:11], 0, v[176:177]
	v_lshl_add_u64 v[134:135], v[134:135], 0, v[164:165]
	v_lshl_add_u64 v[176:177], v[162:163], 1, v[176:177]
	s_waitcnt vmcnt(3)
	v_pk_add_f32 v[126:127], v[126:127], v[132:133]
	v_pk_add_f32 v[124:125], v[124:125], v[130:131]
	s_waitcnt vmcnt(2)
	v_pk_add_f32 v[122:123], v[122:123], v[140:141]
	v_pk_add_f32 v[120:121], v[120:121], v[138:139]
	v_pk_mul_f32 v[132:133], v[94:95], v[126:127]
	v_pk_mul_f32 v[130:131], v[92:93], v[124:125]
	v_pk_mul_f32 v[138:139], v[90:91], v[122:123]
	v_pk_mul_f32 v[140:141], v[88:89], v[120:121]
	v_cvt_pk_bf16_f32 v130, v130, v131
	v_cvt_pk_bf16_f32 v131, v132, v133
	v_cvt_pk_bf16_f32 v132, v140, v141
	v_cvt_pk_bf16_f32 v133, v138, v139
	global_store_dwordx4 v[134:135], v[124:127], off
	global_store_dwordx4 v[134:135], v[120:123], off offset:16
	global_store_dwordx4 v[176:177], v[130:133], off
	s_waitcnt vmcnt(4)
	s_nop 1
	v_mov_b32_e32 v130, v178
	v_mov_b32_e32 v131, v179
	v_mov_b32_e32 v132, v180
	v_mov_b32_e32 v133, v181
	s_nop 0
	s_waitcnt vmcnt(3)
	v_mov_b32_e32 v138, v182
	v_mov_b32_e32 v139, v183
	v_mov_b32_e32 v140, v184
	v_mov_b32_e32 v141, v185
	v_mul_f32_e32 v125, v125, v125
	v_fmac_f32_e32 v125, v124, v124
	v_fmac_f32_e32 v125, v126, v126
	v_fmac_f32_e32 v125, v127, v127
	v_fmac_f32_e32 v125, v120, v120
	v_fmac_f32_e32 v125, v121, v121
	v_fmac_f32_e32 v125, v122, v122
	v_fmac_f32_e32 v125, v123, v123
	v_pk_add_f32 v[116:117], v[116:117], v[130:131]
	s_nop 0
	v_mul_f32_e32 v120, v117, v117
	v_pk_add_f32 v[118:119], v[118:119], v[132:133]
	v_fmac_f32_e32 v120, v116, v116
	v_fmac_f32_e32 v120, v118, v118
	v_pk_add_f32 v[112:113], v[112:113], v[138:139]
	v_fmac_f32_e32 v120, v119, v119
	v_fmac_f32_e32 v120, v112, v112
	v_pk_add_f32 v[114:115], v[114:115], v[140:141]
	v_fmac_f32_e32 v120, v113, v113
	v_fmac_f32_e32 v120, v114, v114
	v_fmac_f32_e32 v120, v115, v115
	v_add_f32_e32 v124, v125, v120
	ds_bpermute_b32 v125, v137, v124
	global_store_dwordx4 v[134:135], v[116:119], off offset:512
	global_store_dwordx4 v[134:135], v[112:115], off offset:528
	v_pk_mul_f32 v[122:123], v[80:81], v[112:113]
	v_pk_mul_f32 v[118:119], v[86:87], v[118:119]
	v_pk_mul_f32 v[116:117], v[84:85], v[116:117]
	s_waitcnt lgkmcnt(0)
	v_add_f32_e32 v112, v124, v125
	ds_bpermute_b32 v113, v136, v112
	v_pk_mul_f32 v[120:121], v[82:83], v[114:115]
	v_cvt_pk_bf16_f32 v114, v116, v117
	v_cvt_pk_bf16_f32 v115, v118, v119
	v_cvt_pk_bf16_f32 v116, v122, v123
	v_cvt_pk_bf16_f32 v117, v120, v121
	global_store_dwordx4 v[176:177], v[114:117], off offset:256
	s_and_saveexec_b64 s[22:23], s[4:5]
	s_cbranch_execz .LBB0_371
	s_waitcnt lgkmcnt(0)
	v_add_f32_e32 v114, v112, v113
	v_lshl_add_u64 v[112:113], v[128:129], 2, s[48:49]
	global_atomic_add_f32 v[112:113], v114, off
.LBB0_371:
	s_or_b64 exec, exec, s[22:23]
	v_or_b32_e32 v112, 32, v166
	s_waitcnt lgkmcnt(0)
	v_ashrrev_i32_e32 v113, 31, v112
	v_add_u32_e32 v152, 0xffffc020, v166
	v_lshlrev_b64 v[122:123], 13, v[112:113]
	v_lshlrev_b64 v[116:117], 13, v[152:153]
	v_lshl_add_u64 v[114:115], s[40:41], 0, v[122:123]
	v_lshl_add_u64 v[116:117], s[42:43], 0, v[116:117]
	v_cmp_gt_i32_e32 vcc, s55, v112
	v_lshlrev_b64 v[126:127], 12, v[112:113]
	v_lshl_add_u64 v[122:123], s[36:37], 0, v[122:123]
	v_cndmask_b32_e32 v115, v117, v115, vcc
	v_cndmask_b32_e32 v114, v116, v114, vcc
	v_lshl_add_u64 v[124:125], v[114:115], 0, v[164:165]
	global_load_dwordx4 v[114:117], v[124:125], off
	global_load_dwordx4 v[118:121], v[124:125], off offset:16
	global_load_dwordx4 v[178:181], v[124:125], off offset:512
	global_load_dwordx4 v[182:185], v[124:125], off offset:528
	v_lshl_add_u64 v[126:127], s[10:11], 0, v[126:127]
	v_lshl_add_u64 v[122:123], v[122:123], 0, v[164:165]
	v_lshl_add_u64 v[126:127], v[162:163], 1, v[126:127]
	s_waitcnt vmcnt(3)
	v_pk_add_f32 v[110:111], v[110:111], v[116:117]
	v_pk_add_f32 v[108:109], v[108:109], v[114:115]
	s_waitcnt vmcnt(2)
	v_pk_add_f32 v[106:107], v[106:107], v[120:121]
	v_pk_add_f32 v[104:105], v[104:105], v[118:119]
	v_pk_mul_f32 v[116:117], v[94:95], v[110:111]
	v_pk_mul_f32 v[114:115], v[92:93], v[108:109]
	v_pk_mul_f32 v[118:119], v[90:91], v[106:107]
	v_pk_mul_f32 v[120:121], v[88:89], v[104:105]
	v_cvt_pk_bf16_f32 v114, v114, v115
	v_cvt_pk_bf16_f32 v115, v116, v117
	v_cvt_pk_bf16_f32 v116, v120, v121
	v_cvt_pk_bf16_f32 v117, v118, v119
	global_store_dwordx4 v[122:123], v[108:111], off
	global_store_dwordx4 v[122:123], v[104:107], off offset:16
	global_store_dwordx4 v[126:127], v[114:117], off
	s_waitcnt vmcnt(4)
	s_nop 1
	v_mov_b32_e32 v114, v178
	v_mov_b32_e32 v115, v179
	v_mov_b32_e32 v116, v180
	v_mov_b32_e32 v117, v181
	s_nop 0
	s_waitcnt vmcnt(3)
	v_mov_b32_e32 v118, v182
	v_mov_b32_e32 v119, v183
	v_mov_b32_e32 v120, v184
	v_mov_b32_e32 v121, v185
	v_mul_f32_e32 v109, v109, v109
	v_fmac_f32_e32 v109, v108, v108
	v_fmac_f32_e32 v109, v110, v110
	v_fmac_f32_e32 v109, v111, v111
	v_fmac_f32_e32 v109, v104, v104
	v_fmac_f32_e32 v109, v105, v105
	v_fmac_f32_e32 v109, v106, v106
	v_fmac_f32_e32 v109, v107, v107
	v_pk_add_f32 v[100:101], v[100:101], v[114:115]
	s_nop 0
	v_mul_f32_e32 v104, v101, v101
	v_pk_add_f32 v[102:103], v[102:103], v[116:117]
	v_fmac_f32_e32 v104, v100, v100
	v_fmac_f32_e32 v104, v102, v102
	v_pk_add_f32 v[96:97], v[96:97], v[118:119]
	v_fmac_f32_e32 v104, v103, v103
	v_fmac_f32_e32 v104, v96, v96
	v_pk_add_f32 v[98:99], v[98:99], v[120:121]
	v_fmac_f32_e32 v104, v97, v97
	v_fmac_f32_e32 v104, v98, v98
	v_fmac_f32_e32 v104, v99, v99
	v_add_f32_e32 v108, v109, v104
	ds_bpermute_b32 v109, v137, v108
	global_store_dwordx4 v[122:123], v[100:103], off offset:512
	global_store_dwordx4 v[122:123], v[96:99], off offset:528
	v_pk_mul_f32 v[106:107], v[80:81], v[96:97]
	v_pk_mul_f32 v[102:103], v[86:87], v[102:103]
	v_pk_mul_f32 v[100:101], v[84:85], v[100:101]
	s_waitcnt lgkmcnt(0)
	v_add_f32_e32 v96, v108, v109
	ds_bpermute_b32 v97, v136, v96
	v_pk_mul_f32 v[104:105], v[82:83], v[98:99]
	v_cvt_pk_bf16_f32 v98, v100, v101
	v_cvt_pk_bf16_f32 v99, v102, v103
	v_cvt_pk_bf16_f32 v100, v106, v107
	v_cvt_pk_bf16_f32 v101, v104, v105
	global_store_dwordx4 v[126:127], v[98:101], off offset:256
	s_and_saveexec_b64 s[22:23], s[4:5]
	s_cbranch_execz .LBB0_373
; DI u32 pack2(float a, float b) { f32v2 v = {a, b}; return __builtin_bit_cast(u32, __builtin_convertvector(v, bf16v2)); }
;   DI void operator()(const f32x4 (&acc)[2][2][4][2], const Unit& u, int wr, int wc, int fr, int fq) const {
;     ...
;     for (int ai = 0; ai < 2; ++ai)
; #pragma unroll
;       for (int m = 0; m < 4; ++m) {
;         const int row = row0 + ai * HALF + m * 16;
;         float* dst = out + (size_t)row * DM + col0;
;         const float* src = layer == 0 ? (row < PROWS ? xp + (size_t)row * DM + col0 : xs + (size_t)(row - PROWS) * DM + col0) : dst;
;         float ss = 0.f;
; #pragma unroll
;         for (int bj = 0; bj < 2; ++bj) {
;           const f32x4 x0 = *reinterpret_cast<const f32x4*>(src + bj * HALF), x1 = *reinterpret_cast<const f32x4*>(src + bj * HALF + 4);
;           const f32x4 n0 = x0 + acc[ai][bj][m][0], n1 = x1 + acc[ai][bj][m][1];
;           *reinterpret_cast<f32x4*>(dst + bj * HALF) = n0; *reinterpret_cast<f32x4*>(dst + bj * HALF + 4) = n1;
;           ss += n0[0] * n0[0] + n0[1] * n0[1] + n0[2] * n0[2] + n0[3] * n0[3] + n1[0] * n1[0] + n1[1] * n1[1] + n1[2] * n1[2] + n1[3] * n1[3];
;           if (xw) {
;             const f32x4 h0 = n0 * wv[bj][0], h1 = n1 * wv[bj][1];
;             u32x4 pk = {pack2(h0[0], h0[1]), pack2(h0[2], h0[3]), pack2(h1[0], h1[1]), pack2(h1[2], h1[3])};
;             *reinterpret_cast<u32x4*>(xw + (size_t)row * DM + col0 + bj * HALF) = pk;
;           }
;         }
;         ss += __shfl_xor(ss, 16); ss += __shfl_xor(ss, 32);
;         if (fq == 0) atomicAdd(rs + row, ss);
;       }
	s_waitcnt lgkmcnt(0)
	v_add_f32_e32 v98, v96, v97
	v_lshl_add_u64 v[96:97], v[112:113], 2, s[48:49]
	global_atomic_add_f32 v[96:97], v98, off
.LBB0_373:
	s_or_b64 exec, exec, s[22:23]
	v_or_b32_e32 v96, 48, v166
	s_waitcnt lgkmcnt(0)
	v_ashrrev_i32_e32 v97, 31, v96
	v_add_u32_e32 v152, 0xffffc030, v166
	v_lshlrev_b64 v[106:107], 13, v[96:97]
	v_lshlrev_b64 v[100:101], 13, v[152:153]
	v_lshl_add_u64 v[98:99], s[40:41], 0, v[106:107]
	v_lshl_add_u64 v[100:101], s[42:43], 0, v[100:101]
	v_cmp_gt_i32_e32 vcc, s55, v96
	v_lshlrev_b64 v[110:111], 12, v[96:97]
	v_lshl_add_u64 v[106:107], s[36:37], 0, v[106:107]
	v_cndmask_b32_e32 v99, v101, v99, vcc
	v_cndmask_b32_e32 v98, v100, v98, vcc
	v_lshl_add_u64 v[108:109], v[98:99], 0, v[164:165]
	global_load_dwordx4 v[98:101], v[108:109], off
	global_load_dwordx4 v[102:105], v[108:109], off offset:16
	global_load_dwordx4 v[178:181], v[108:109], off offset:512
	global_load_dwordx4 v[182:185], v[108:109], off offset:528
	v_lshl_add_u64 v[110:111], s[10:11], 0, v[110:111]
	v_lshl_add_u64 v[106:107], v[106:107], 0, v[164:165]
	v_lshl_add_u64 v[110:111], v[162:163], 1, v[110:111]
	s_waitcnt vmcnt(3)
	v_pk_add_f32 v[78:79], v[78:79], v[100:101]
	v_pk_add_f32 v[76:77], v[76:77], v[98:99]
	s_waitcnt vmcnt(2)
	v_pk_add_f32 v[74:75], v[74:75], v[104:105]
	v_pk_add_f32 v[72:73], v[72:73], v[102:103]
	v_pk_mul_f32 v[100:101], v[94:95], v[78:79]
	v_pk_mul_f32 v[98:99], v[92:93], v[76:77]
	v_pk_mul_f32 v[102:103], v[90:91], v[74:75]
	v_pk_mul_f32 v[104:105], v[88:89], v[72:73]
	v_cvt_pk_bf16_f32 v98, v98, v99
	v_cvt_pk_bf16_f32 v99, v100, v101
	v_cvt_pk_bf16_f32 v100, v104, v105
	v_cvt_pk_bf16_f32 v101, v102, v103
	global_store_dwordx4 v[106:107], v[76:79], off
	global_store_dwordx4 v[106:107], v[72:75], off offset:16
	global_store_dwordx4 v[110:111], v[98:101], off
	s_waitcnt vmcnt(4)
	s_nop 1
	v_mov_b32_e32 v98, v178
	v_mov_b32_e32 v99, v179
	v_mov_b32_e32 v100, v180
	v_mov_b32_e32 v101, v181
	s_nop 0
	s_waitcnt vmcnt(3)
	v_mov_b32_e32 v102, v182
	v_mov_b32_e32 v103, v183
	v_mov_b32_e32 v104, v184
	v_mov_b32_e32 v105, v185
	v_mul_f32_e32 v77, v77, v77
	v_fmac_f32_e32 v77, v76, v76
	v_fmac_f32_e32 v77, v78, v78
	v_fmac_f32_e32 v77, v79, v79
	v_fmac_f32_e32 v77, v72, v72
	v_fmac_f32_e32 v77, v73, v73
	v_fmac_f32_e32 v77, v74, v74
	v_fmac_f32_e32 v77, v75, v75
	v_pk_add_f32 v[68:69], v[68:69], v[98:99]
	s_nop 0
	v_mul_f32_e32 v72, v69, v69
	v_pk_add_f32 v[70:71], v[70:71], v[100:101]
	v_fmac_f32_e32 v72, v68, v68
	v_fmac_f32_e32 v72, v70, v70
	v_pk_add_f32 v[64:65], v[64:65], v[102:103]
	v_fmac_f32_e32 v72, v71, v71
	v_fmac_f32_e32 v72, v64, v64
	v_pk_add_f32 v[66:67], v[66:67], v[104:105]
	v_fmac_f32_e32 v72, v65, v65
	v_fmac_f32_e32 v72, v66, v66
	v_fmac_f32_e32 v72, v67, v67
	v_add_f32_e32 v76, v77, v72
	ds_bpermute_b32 v77, v137, v76
	global_store_dwordx4 v[106:107], v[68:71], off offset:512
	global_store_dwordx4 v[106:107], v[64:67], off offset:528
	v_pk_mul_f32 v[74:75], v[80:81], v[64:65]
	v_pk_mul_f32 v[70:71], v[86:87], v[70:71]
	v_pk_mul_f32 v[68:69], v[84:85], v[68:69]
	s_waitcnt lgkmcnt(0)
	v_add_f32_e32 v64, v76, v77
	ds_bpermute_b32 v65, v136, v64
	v_pk_mul_f32 v[72:73], v[82:83], v[66:67]
	v_cvt_pk_bf16_f32 v66, v68, v69
	v_cvt_pk_bf16_f32 v67, v70, v71
	v_cvt_pk_bf16_f32 v68, v74, v75
	v_cvt_pk_bf16_f32 v69, v72, v73
	global_store_dwordx4 v[110:111], v[66:69], off offset:256
	s_and_saveexec_b64 s[22:23], s[4:5]
	s_cbranch_execz .LBB0_375
	s_waitcnt lgkmcnt(0)
	v_add_f32_e32 v66, v64, v65
	v_lshl_add_u64 v[64:65], v[96:97], 2, s[48:49]
	global_atomic_add_f32 v[64:65], v66, off
.LBB0_375:
	s_or_b64 exec, exec, s[22:23]
	v_add_u32_e32 v64, 0x80, v166
	s_waitcnt lgkmcnt(0)
	v_ashrrev_i32_e32 v65, 31, v64
	v_add_u32_e32 v152, 0xffffc080, v166
	v_lshlrev_b64 v[74:75], 13, v[64:65]
	v_lshlrev_b64 v[68:69], 13, v[152:153]
	v_lshl_add_u64 v[66:67], s[40:41], 0, v[74:75]
	v_lshl_add_u64 v[68:69], s[42:43], 0, v[68:69]
	v_cmp_gt_i32_e32 vcc, s68, v166
	v_lshlrev_b64 v[78:79], 12, v[64:65]
	v_lshl_add_u64 v[74:75], s[36:37], 0, v[74:75]
	v_cndmask_b32_e32 v67, v69, v67, vcc
	v_cndmask_b32_e32 v66, v68, v66, vcc
	v_lshl_add_u64 v[76:77], v[66:67], 0, v[164:165]
	global_load_dwordx4 v[66:69], v[76:77], off
	global_load_dwordx4 v[70:73], v[76:77], off offset:16
	global_load_dwordx4 v[178:181], v[76:77], off offset:512
	global_load_dwordx4 v[182:185], v[76:77], off offset:528
	v_lshl_add_u64 v[78:79], s[10:11], 0, v[78:79]
	v_lshl_add_u64 v[74:75], v[74:75], 0, v[164:165]
	v_lshl_add_u64 v[78:79], v[162:163], 1, v[78:79]
	s_waitcnt vmcnt(3)
	v_pk_add_f32 v[62:63], v[62:63], v[68:69]
	v_pk_add_f32 v[60:61], v[60:61], v[66:67]
	s_waitcnt vmcnt(2)
	v_pk_add_f32 v[58:59], v[58:59], v[72:73]
	v_pk_add_f32 v[56:57], v[56:57], v[70:71]
	v_pk_mul_f32 v[68:69], v[94:95], v[62:63]
	v_pk_mul_f32 v[66:67], v[92:93], v[60:61]
	v_pk_mul_f32 v[70:71], v[90:91], v[58:59]
	v_pk_mul_f32 v[72:73], v[88:89], v[56:57]
	v_cvt_pk_bf16_f32 v66, v66, v67
	v_cvt_pk_bf16_f32 v67, v68, v69
	v_cvt_pk_bf16_f32 v68, v72, v73
	v_cvt_pk_bf16_f32 v69, v70, v71
	global_store_dwordx4 v[74:75], v[60:63], off
	global_store_dwordx4 v[74:75], v[56:59], off offset:16
	global_store_dwordx4 v[78:79], v[66:69], off
	s_waitcnt vmcnt(4)
	s_nop 1
	v_mov_b32_e32 v66, v178
	v_mov_b32_e32 v67, v179
	v_mov_b32_e32 v68, v180
	v_mov_b32_e32 v69, v181
	s_nop 0
	s_waitcnt vmcnt(3)
	v_mov_b32_e32 v70, v182
	v_mov_b32_e32 v71, v183
	v_mov_b32_e32 v72, v184
	v_mov_b32_e32 v73, v185
	v_mul_f32_e32 v61, v61, v61
	v_fmac_f32_e32 v61, v60, v60
	v_fmac_f32_e32 v61, v62, v62
	v_fmac_f32_e32 v61, v63, v63
	v_fmac_f32_e32 v61, v56, v56
	v_fmac_f32_e32 v61, v57, v57
	v_fmac_f32_e32 v61, v58, v58
	v_fmac_f32_e32 v61, v59, v59
	v_pk_add_f32 v[52:53], v[52:53], v[66:67]
	s_nop 0
	v_mul_f32_e32 v56, v53, v53
	v_pk_add_f32 v[54:55], v[54:55], v[68:69]
	v_fmac_f32_e32 v56, v52, v52
	v_fmac_f32_e32 v56, v54, v54
	v_pk_add_f32 v[48:49], v[48:49], v[70:71]
	v_fmac_f32_e32 v56, v55, v55
	v_fmac_f32_e32 v56, v48, v48
	v_pk_add_f32 v[50:51], v[50:51], v[72:73]
	v_fmac_f32_e32 v56, v49, v49
	v_fmac_f32_e32 v56, v50, v50
	v_fmac_f32_e32 v56, v51, v51
	v_add_f32_e32 v60, v61, v56
	ds_bpermute_b32 v61, v137, v60
	global_store_dwordx4 v[74:75], v[52:55], off offset:512
	global_store_dwordx4 v[74:75], v[48:51], off offset:528
	v_pk_mul_f32 v[58:59], v[80:81], v[48:49]
	v_pk_mul_f32 v[54:55], v[86:87], v[54:55]
	v_pk_mul_f32 v[52:53], v[84:85], v[52:53]
	s_waitcnt lgkmcnt(0)
	v_add_f32_e32 v48, v60, v61
	ds_bpermute_b32 v49, v136, v48
	v_pk_mul_f32 v[56:57], v[82:83], v[50:51]
	v_cvt_pk_bf16_f32 v50, v52, v53
	v_cvt_pk_bf16_f32 v51, v54, v55
	v_cvt_pk_bf16_f32 v52, v58, v59
	v_cvt_pk_bf16_f32 v53, v56, v57
	global_store_dwordx4 v[78:79], v[50:53], off offset:256
	s_and_saveexec_b64 s[22:23], s[4:5]
	s_cbranch_execz .LBB0_377
	s_waitcnt lgkmcnt(0)
	v_add_f32_e32 v50, v48, v49
	v_lshl_add_u64 v[48:49], v[64:65], 2, s[48:49]
	global_atomic_add_f32 v[48:49], v50, off
; DI u32 pack2(float a, float b) { f32v2 v = {a, b}; return __builtin_bit_cast(u32, __builtin_convertvector(v, bf16v2)); }
;   DI void operator()(const f32x4 (&acc)[2][2][4][2], const Unit& u, int wr, int wc, int fr, int fq) const {
;     ...
;     for (int ai = 0; ai < 2; ++ai)
; #pragma unroll
;       for (int m = 0; m < 4; ++m) {
;         const int row = row0 + ai * HALF + m * 16;
;         float* dst = out + (size_t)row * DM + col0;
;         const float* src = layer == 0 ? (row < PROWS ? xp + (size_t)row * DM + col0 : xs + (size_t)(row - PROWS) * DM + col0) : dst;
;         float ss = 0.f;
; #pragma unroll
;         for (int bj = 0; bj < 2; ++bj) {
;           const f32x4 x0 = *reinterpret_cast<const f32x4*>(src + bj * HALF), x1 = *reinterpret_cast<const f32x4*>(src + bj * HALF + 4);
;           const f32x4 n0 = x0 + acc[ai][bj][m][0], n1 = x1 + acc[ai][bj][m][1];
;           *reinterpret_cast<f32x4*>(dst + bj * HALF) = n0; *reinterpret_cast<f32x4*>(dst + bj * HALF + 4) = n1;
;           ss += n0[0] * n0[0] + n0[1] * n0[1] + n0[2] * n0[2] + n0[3] * n0[3] + n1[0] * n1[0] + n1[1] * n1[1] + n1[2] * n1[2] + n1[3] * n1[3];
;           if (xw) {
;             const f32x4 h0 = n0 * wv[bj][0], h1 = n1 * wv[bj][1];
;             u32x4 pk = {pack2(h0[0], h0[1]), pack2(h0[2], h0[3]), pack2(h1[0], h1[1]), pack2(h1[2], h1[3])};
;             *reinterpret_cast<u32x4*>(xw + (size_t)row * DM + col0 + bj * HALF) = pk;
;           }
;         }
;         ss += __shfl_xor(ss, 16); ss += __shfl_xor(ss, 32);
;         if (fq == 0) atomicAdd(rs + row, ss);
;       }
.LBB0_377:
	s_or_b64 exec, exec, s[22:23]
	v_add_u32_e32 v48, 0x90, v166
	s_waitcnt lgkmcnt(0)
	v_ashrrev_i32_e32 v49, 31, v48
	v_add_u32_e32 v152, 0xffffc090, v166
	v_lshlrev_b64 v[58:59], 13, v[48:49]
	v_lshlrev_b64 v[52:53], 13, v[152:153]
	v_lshl_add_u64 v[50:51], s[40:41], 0, v[58:59]
	v_lshl_add_u64 v[52:53], s[42:43], 0, v[52:53]
	v_cmp_gt_i32_e32 vcc, s69, v166
	v_lshlrev_b64 v[62:63], 12, v[48:49]
	v_lshl_add_u64 v[58:59], s[36:37], 0, v[58:59]
	v_cndmask_b32_e32 v51, v53, v51, vcc
	v_cndmask_b32_e32 v50, v52, v50, vcc
	v_lshl_add_u64 v[60:61], v[50:51], 0, v[164:165]
	global_load_dwordx4 v[50:53], v[60:61], off
	global_load_dwordx4 v[54:57], v[60:61], off offset:16
	global_load_dwordx4 v[178:181], v[60:61], off offset:512
	global_load_dwordx4 v[182:185], v[60:61], off offset:528
	v_lshl_add_u64 v[62:63], s[10:11], 0, v[62:63]
	v_lshl_add_u64 v[58:59], v[58:59], 0, v[164:165]
	v_lshl_add_u64 v[62:63], v[162:163], 1, v[62:63]
	s_waitcnt vmcnt(3)
	v_pk_add_f32 v[46:47], v[46:47], v[52:53]
	v_pk_add_f32 v[44:45], v[44:45], v[50:51]
	s_waitcnt vmcnt(2)
	v_pk_add_f32 v[42:43], v[42:43], v[56:57]
	v_pk_add_f32 v[40:41], v[40:41], v[54:55]
	v_pk_mul_f32 v[52:53], v[94:95], v[46:47]
	v_pk_mul_f32 v[50:51], v[92:93], v[44:45]
	v_pk_mul_f32 v[54:55], v[90:91], v[42:43]
	v_pk_mul_f32 v[56:57], v[88:89], v[40:41]
	v_cvt_pk_bf16_f32 v50, v50, v51
	v_cvt_pk_bf16_f32 v51, v52, v53
	v_cvt_pk_bf16_f32 v52, v56, v57
	v_cvt_pk_bf16_f32 v53, v54, v55
	global_store_dwordx4 v[58:59], v[44:47], off
	global_store_dwordx4 v[58:59], v[40:43], off offset:16
	global_store_dwordx4 v[62:63], v[50:53], off
	s_waitcnt vmcnt(4)
	s_nop 1
	v_mov_b32_e32 v50, v178
	v_mov_b32_e32 v51, v179
	v_mov_b32_e32 v52, v180
	v_mov_b32_e32 v53, v181
	s_nop 0
	s_waitcnt vmcnt(3)
	v_mov_b32_e32 v54, v182
	v_mov_b32_e32 v55, v183
	v_mov_b32_e32 v56, v184
	v_mov_b32_e32 v57, v185
	v_mul_f32_e32 v45, v45, v45
	v_fmac_f32_e32 v45, v44, v44
	v_fmac_f32_e32 v45, v46, v46
	v_fmac_f32_e32 v45, v47, v47
	v_fmac_f32_e32 v45, v40, v40
	v_fmac_f32_e32 v45, v41, v41
	v_fmac_f32_e32 v45, v42, v42
	v_fmac_f32_e32 v45, v43, v43
	v_pk_add_f32 v[36:37], v[36:37], v[50:51]
	s_nop 0
	v_mul_f32_e32 v40, v37, v37
	v_pk_add_f32 v[38:39], v[38:39], v[52:53]
	v_fmac_f32_e32 v40, v36, v36
	v_fmac_f32_e32 v40, v38, v38
	v_pk_add_f32 v[32:33], v[32:33], v[54:55]
	v_fmac_f32_e32 v40, v39, v39
	v_fmac_f32_e32 v40, v32, v32
	v_pk_add_f32 v[34:35], v[34:35], v[56:57]
	v_fmac_f32_e32 v40, v33, v33
	v_fmac_f32_e32 v40, v34, v34
	v_fmac_f32_e32 v40, v35, v35
	v_add_f32_e32 v44, v45, v40
	ds_bpermute_b32 v45, v137, v44
	global_store_dwordx4 v[58:59], v[36:39], off offset:512
	global_store_dwordx4 v[58:59], v[32:35], off offset:528
	v_pk_mul_f32 v[42:43], v[80:81], v[32:33]
	v_pk_mul_f32 v[38:39], v[86:87], v[38:39]
	v_pk_mul_f32 v[36:37], v[84:85], v[36:37]
	s_waitcnt lgkmcnt(0)
	v_add_f32_e32 v32, v44, v45
	ds_bpermute_b32 v33, v136, v32
	v_pk_mul_f32 v[40:41], v[82:83], v[34:35]
	v_cvt_pk_bf16_f32 v34, v36, v37
	v_cvt_pk_bf16_f32 v35, v38, v39
	v_cvt_pk_bf16_f32 v36, v42, v43
	v_cvt_pk_bf16_f32 v37, v40, v41
	global_store_dwordx4 v[62:63], v[34:37], off offset:256
	s_and_saveexec_b64 s[22:23], s[4:5]
	s_cbranch_execz .LBB0_379
	s_waitcnt lgkmcnt(0)
	v_add_f32_e32 v34, v32, v33
	v_lshl_add_u64 v[32:33], v[48:49], 2, s[48:49]
	global_atomic_add_f32 v[32:33], v34, off
; DI u32 pack2(float a, float b) { f32v2 v = {a, b}; return __builtin_bit_cast(u32, __builtin_convertvector(v, bf16v2)); }
;   DI void operator()(const f32x4 (&acc)[2][2][4][2], const Unit& u, int wr, int wc, int fr, int fq) const {
;     ...
;     for (int ai = 0; ai < 2; ++ai)
; #pragma unroll
;       for (int m = 0; m < 4; ++m) {
;         const int row = row0 + ai * HALF + m * 16;
;         float* dst = out + (size_t)row * DM + col0;
;         const float* src = layer == 0 ? (row < PROWS ? xp + (size_t)row * DM + col0 : xs + (size_t)(row - PROWS) * DM + col0) : dst;
;         float ss = 0.f;
; #pragma unroll
;         for (int bj = 0; bj < 2; ++bj) {
;           const f32x4 x0 = *reinterpret_cast<const f32x4*>(src + bj * HALF), x1 = *reinterpret_cast<const f32x4*>(src + bj * HALF + 4);
;           const f32x4 n0 = x0 + acc[ai][bj][m][0], n1 = x1 + acc[ai][bj][m][1];
;           *reinterpret_cast<f32x4*>(dst + bj * HALF) = n0; *reinterpret_cast<f32x4*>(dst + bj * HALF + 4) = n1;
;           ss += n0[0] * n0[0] + n0[1] * n0[1] + n0[2] * n0[2] + n0[3] * n0[3] + n1[0] * n1[0] + n1[1] * n1[1] + n1[2] * n1[2] + n1[3] * n1[3];
;           if (xw) {
;             const f32x4 h0 = n0 * wv[bj][0], h1 = n1 * wv[bj][1];
;             u32x4 pk = {pack2(h0[0], h0[1]), pack2(h0[2], h0[3]), pack2(h1[0], h1[1]), pack2(h1[2], h1[3])};
;             *reinterpret_cast<u32x4*>(xw + (size_t)row * DM + col0 + bj * HALF) = pk;
;           }
;         }
;         ss += __shfl_xor(ss, 16); ss += __shfl_xor(ss, 32);
;         if (fq == 0) atomicAdd(rs + row, ss);
;       }
.LBB0_379:
	s_or_b64 exec, exec, s[22:23]
	v_add_u32_e32 v32, 0xa0, v166
	s_waitcnt lgkmcnt(0)
	v_ashrrev_i32_e32 v33, 31, v32
	v_add_u32_e32 v152, 0xffffc0a0, v166
	v_lshlrev_b64 v[42:43], 13, v[32:33]
	v_lshlrev_b64 v[36:37], 13, v[152:153]
	v_lshl_add_u64 v[34:35], s[40:41], 0, v[42:43]
	v_lshl_add_u64 v[36:37], s[42:43], 0, v[36:37]
	v_cmp_gt_i32_e32 vcc, s70, v166
	v_lshlrev_b64 v[46:47], 12, v[32:33]
	v_lshl_add_u64 v[42:43], s[36:37], 0, v[42:43]
	v_cndmask_b32_e32 v35, v37, v35, vcc
	v_cndmask_b32_e32 v34, v36, v34, vcc
	v_lshl_add_u64 v[44:45], v[34:35], 0, v[164:165]
	global_load_dwordx4 v[34:37], v[44:45], off
	global_load_dwordx4 v[38:41], v[44:45], off offset:16
	global_load_dwordx4 v[178:181], v[44:45], off offset:512
	global_load_dwordx4 v[182:185], v[44:45], off offset:528
	v_lshl_add_u64 v[46:47], s[10:11], 0, v[46:47]
	v_lshl_add_u64 v[42:43], v[42:43], 0, v[164:165]
	v_lshl_add_u64 v[46:47], v[162:163], 1, v[46:47]
	s_waitcnt vmcnt(3)
	v_pk_add_f32 v[30:31], v[30:31], v[36:37]
	v_pk_add_f32 v[28:29], v[28:29], v[34:35]
	s_waitcnt vmcnt(2)
	v_pk_add_f32 v[26:27], v[26:27], v[40:41]
	v_pk_add_f32 v[24:25], v[24:25], v[38:39]
	v_pk_mul_f32 v[36:37], v[94:95], v[30:31]
	v_pk_mul_f32 v[34:35], v[92:93], v[28:29]
	v_pk_mul_f32 v[38:39], v[90:91], v[26:27]
	v_pk_mul_f32 v[40:41], v[88:89], v[24:25]
	v_cvt_pk_bf16_f32 v34, v34, v35
	v_cvt_pk_bf16_f32 v35, v36, v37
	v_cvt_pk_bf16_f32 v36, v40, v41
	v_cvt_pk_bf16_f32 v37, v38, v39
	global_store_dwordx4 v[42:43], v[28:31], off
	global_store_dwordx4 v[42:43], v[24:27], off offset:16
	global_store_dwordx4 v[46:47], v[34:37], off
	s_waitcnt vmcnt(4)
	s_nop 1
	v_mov_b32_e32 v34, v178
	v_mov_b32_e32 v35, v179
	v_mov_b32_e32 v36, v180
	v_mov_b32_e32 v37, v181
	s_nop 0
	s_waitcnt vmcnt(3)
	v_mov_b32_e32 v38, v182
	v_mov_b32_e32 v39, v183
	v_mov_b32_e32 v40, v184
	v_mov_b32_e32 v41, v185
	v_mul_f32_e32 v29, v29, v29
	v_fmac_f32_e32 v29, v28, v28
	v_fmac_f32_e32 v29, v30, v30
	v_fmac_f32_e32 v29, v31, v31
	v_fmac_f32_e32 v29, v24, v24
	v_fmac_f32_e32 v29, v25, v25
	v_fmac_f32_e32 v29, v26, v26
	v_fmac_f32_e32 v29, v27, v27
	v_pk_add_f32 v[20:21], v[20:21], v[34:35]
	s_nop 0
	v_mul_f32_e32 v24, v21, v21
	v_pk_add_f32 v[22:23], v[22:23], v[36:37]
	v_fmac_f32_e32 v24, v20, v20
	v_fmac_f32_e32 v24, v22, v22
	v_pk_add_f32 v[16:17], v[16:17], v[38:39]
	v_fmac_f32_e32 v24, v23, v23
	v_fmac_f32_e32 v24, v16, v16
	v_pk_add_f32 v[18:19], v[18:19], v[40:41]
	v_fmac_f32_e32 v24, v17, v17
	v_fmac_f32_e32 v24, v18, v18
	v_fmac_f32_e32 v24, v19, v19
	v_add_f32_e32 v28, v29, v24
	ds_bpermute_b32 v29, v137, v28
	global_store_dwordx4 v[42:43], v[20:23], off offset:512
	global_store_dwordx4 v[42:43], v[16:19], off offset:528
	v_pk_mul_f32 v[26:27], v[80:81], v[16:17]
	v_pk_mul_f32 v[22:23], v[86:87], v[22:23]
	v_pk_mul_f32 v[20:21], v[84:85], v[20:21]
	s_waitcnt lgkmcnt(0)
	v_add_f32_e32 v16, v28, v29
	ds_bpermute_b32 v17, v136, v16
	v_pk_mul_f32 v[24:25], v[82:83], v[18:19]
	v_cvt_pk_bf16_f32 v18, v20, v21
	v_cvt_pk_bf16_f32 v19, v22, v23
	v_cvt_pk_bf16_f32 v20, v26, v27
	v_cvt_pk_bf16_f32 v21, v24, v25
	global_store_dwordx4 v[46:47], v[18:21], off offset:256
	s_and_saveexec_b64 s[22:23], s[4:5]
	s_cbranch_execz .LBB0_381
	s_waitcnt lgkmcnt(0)
	v_add_f32_e32 v18, v16, v17
	v_lshl_add_u64 v[16:17], v[32:33], 2, s[48:49]
	global_atomic_add_f32 v[16:17], v18, off
.LBB0_381:
	s_or_b64 exec, exec, s[22:23]
	v_add_u32_e32 v16, 0xb0, v166
	s_waitcnt lgkmcnt(0)
	v_ashrrev_i32_e32 v17, 31, v16
	v_add_u32_e32 v152, 0xffffc0b0, v166
	v_lshlrev_b64 v[26:27], 13, v[16:17]
	v_lshlrev_b64 v[20:21], 13, v[152:153]
	v_lshl_add_u64 v[18:19], s[40:41], 0, v[26:27]
	v_lshl_add_u64 v[20:21], s[42:43], 0, v[20:21]
	v_cmp_gt_i32_e32 vcc, s71, v166
	v_lshlrev_b64 v[30:31], 12, v[16:17]
	v_lshl_add_u64 v[26:27], s[36:37], 0, v[26:27]
	v_cndmask_b32_e32 v19, v21, v19, vcc
	v_cndmask_b32_e32 v18, v20, v18, vcc
	v_lshl_add_u64 v[28:29], v[18:19], 0, v[164:165]
	global_load_dwordx4 v[18:21], v[28:29], off
	global_load_dwordx4 v[22:25], v[28:29], off offset:16
	global_load_dwordx4 v[178:181], v[28:29], off offset:512
	global_load_dwordx4 v[182:185], v[28:29], off offset:528
	v_lshl_add_u64 v[30:31], s[10:11], 0, v[30:31]
	v_lshl_add_u64 v[26:27], v[26:27], 0, v[164:165]
	v_lshl_add_u64 v[30:31], v[162:163], 1, v[30:31]
	s_waitcnt vmcnt(3)
	v_pk_add_f32 v[14:15], v[14:15], v[20:21]
	v_pk_add_f32 v[12:13], v[12:13], v[18:19]
	s_waitcnt vmcnt(2)
	v_pk_add_f32 v[10:11], v[10:11], v[24:25]
	v_pk_add_f32 v[8:9], v[8:9], v[22:23]
	v_pk_mul_f32 v[20:21], v[94:95], v[14:15]
	v_pk_mul_f32 v[18:19], v[92:93], v[12:13]
	v_pk_mul_f32 v[22:23], v[90:91], v[10:11]
	v_pk_mul_f32 v[24:25], v[88:89], v[8:9]
	v_cvt_pk_bf16_f32 v18, v18, v19
	v_cvt_pk_bf16_f32 v19, v20, v21
	v_cvt_pk_bf16_f32 v20, v24, v25
	v_cvt_pk_bf16_f32 v21, v22, v23
	global_store_dwordx4 v[26:27], v[12:15], off
	global_store_dwordx4 v[26:27], v[8:11], off offset:16
	global_store_dwordx4 v[30:31], v[18:21], off
	s_waitcnt vmcnt(4)
	s_nop 1
	v_mov_b32_e32 v18, v178
	v_mov_b32_e32 v19, v179
	v_mov_b32_e32 v20, v180
	v_mov_b32_e32 v21, v181
	s_nop 0
	s_waitcnt vmcnt(3)
	v_mov_b32_e32 v22, v182
	v_mov_b32_e32 v23, v183
	v_mov_b32_e32 v24, v184
	v_mov_b32_e32 v25, v185
	v_mul_f32_e32 v13, v13, v13
	v_fmac_f32_e32 v13, v12, v12
	v_fmac_f32_e32 v13, v14, v14
	v_fmac_f32_e32 v13, v15, v15
	v_fmac_f32_e32 v13, v8, v8
	v_fmac_f32_e32 v13, v9, v9
	v_fmac_f32_e32 v13, v10, v10
	v_fmac_f32_e32 v13, v11, v11
	v_pk_add_f32 v[4:5], v[4:5], v[18:19]
	s_nop 0
	v_mul_f32_e32 v8, v5, v5
	v_pk_add_f32 v[6:7], v[6:7], v[20:21]
	v_fmac_f32_e32 v8, v4, v4
	v_fmac_f32_e32 v8, v6, v6
	v_pk_add_f32 v[0:1], v[0:1], v[22:23]
	v_fmac_f32_e32 v8, v7, v7
	v_fmac_f32_e32 v8, v0, v0
	v_pk_add_f32 v[2:3], v[2:3], v[24:25]
	v_fmac_f32_e32 v8, v1, v1
	v_fmac_f32_e32 v8, v2, v2
	v_fmac_f32_e32 v8, v3, v3
	v_add_f32_e32 v12, v13, v8
	ds_bpermute_b32 v13, v137, v12
	global_store_dwordx4 v[26:27], v[4:7], off offset:512
	global_store_dwordx4 v[26:27], v[0:3], off offset:528
	v_pk_mul_f32 v[10:11], v[80:81], v[0:1]
	v_pk_mul_f32 v[6:7], v[86:87], v[6:7]
	v_pk_mul_f32 v[4:5], v[84:85], v[4:5]
	s_waitcnt lgkmcnt(0)
	v_add_f32_e32 v0, v12, v13
	ds_bpermute_b32 v1, v136, v0
	v_pk_mul_f32 v[8:9], v[82:83], v[2:3]
	v_cvt_pk_bf16_f32 v2, v4, v5
	v_cvt_pk_bf16_f32 v3, v6, v7
	v_cvt_pk_bf16_f32 v4, v10, v11
	v_cvt_pk_bf16_f32 v5, v8, v9
	global_store_dwordx4 v[30:31], v[2:5], off offset:256
	s_and_saveexec_b64 s[22:23], s[4:5]
	s_cbranch_execz .LBB0_362
	s_waitcnt lgkmcnt(0)
	v_add_f32_e32 v2, v0, v1
	v_lshl_add_u64 v[0:1], v[16:17], 2, s[48:49]
	global_atomic_add_f32 v[0:1], v2, off
	s_branch .LBB0_362

; DI u32 pack2(float a, float b) { f32v2 v = {a, b}; return __builtin_bit_cast(u32, __builtin_convertvector(v, bf16v2)); }
;   DI void operator()(const f32x4 (&acc)[2][2][4][2], const Unit& u, int wr, int wc, int fr, int fq) const {
;     ...
;     for (int ai = 0; ai < 2; ++ai)
; #pragma unroll
;       for (int m = 0; m < 4; ++m) {
;         const int row = row0 + ai * HALF + m * 16;
;         float* dst = out + (size_t)row * DM + col0;
;         const float* src = layer == 0 ? (row < PROWS ? xp + (size_t)row * DM + col0 : xs + (size_t)(row - PROWS) * DM + col0) : dst;
;         float ss = 0.f;
; #pragma unroll
;         for (int bj = 0; bj < 2; ++bj) {
;           const f32x4 x0 = *reinterpret_cast<const f32x4*>(src + bj * HALF), x1 = *reinterpret_cast<const f32x4*>(src + bj * HALF + 4);
;           const f32x4 n0 = x0 + acc[ai][bj][m][0], n1 = x1 + acc[ai][bj][m][1];
;           *reinterpret_cast<f32x4*>(dst + bj * HALF) = n0; *reinterpret_cast<f32x4*>(dst + bj * HALF + 4) = n1;
;           ss += n0[0] * n0[0] + n0[1] * n0[1] + n0[2] * n0[2] + n0[3] * n0[3] + n1[0] * n1[0] + n1[1] * n1[1] + n1[2] * n1[2] + n1[3] * n1[3];
;           if (xw) {
;             const f32x4 h0 = n0 * wv[bj][0], h1 = n1 * wv[bj][1];
;             u32x4 pk = {pack2(h0[0], h0[1]), pack2(h0[2], h0[3]), pack2(h1[0], h1[1]), pack2(h1[2], h1[3])};
;             *reinterpret_cast<u32x4*>(xw + (size_t)row * DM + col0 + bj * HALF) = pk;
;           }
;         }
;         ss += __shfl_xor(ss, 16); ss += __shfl_xor(ss, 32);
;         if (fq == 0) atomicAdd(rs + row, ss);
;       }
.LBB0_784:
	s_or_b64 exec, exec, s[24:25]
	v_or_b32_e32 v128, 16, v162
	s_waitcnt lgkmcnt(0)
	v_ashrrev_i32_e32 v129, 31, v128
	v_lshlrev_b64 v[130:131], 13, v[128:129]
	v_lshl_add_u64 v[130:131], s[68:69], 0, v[130:131]
	v_lshl_add_u64 v[134:135], v[160:161], 2, v[130:131]
	global_load_dwordx4 v[130:133], v[134:135], off
	global_load_dwordx4 v[138:141], v[134:135], off offset:16
	global_load_dwordx4 v[172:175], v[134:135], off offset:512
	global_load_dwordx4 v[176:179], v[134:135], off offset:528
	v_lshlrev_b64 v[142:143], 12, v[128:129]
	v_lshl_add_u64 v[142:143], s[86:87], 0, v[142:143]
	v_lshl_add_u64 v[142:143], v[160:161], 1, v[142:143]
	s_waitcnt vmcnt(3)
	v_pk_add_f32 v[126:127], v[126:127], v[132:133]
	v_pk_add_f32 v[124:125], v[124:125], v[130:131]
	s_waitcnt vmcnt(2)
	v_pk_add_f32 v[122:123], v[122:123], v[140:141]
	v_pk_add_f32 v[120:121], v[120:121], v[138:139]
	v_pk_mul_f32 v[132:133], v[94:95], v[126:127]
	v_pk_mul_f32 v[130:131], v[92:93], v[124:125]
	v_pk_mul_f32 v[138:139], v[90:91], v[122:123]
	v_pk_mul_f32 v[140:141], v[88:89], v[120:121]
	v_cvt_pk_bf16_f32 v130, v130, v131
	v_cvt_pk_bf16_f32 v131, v132, v133
	v_cvt_pk_bf16_f32 v132, v140, v141
	v_cvt_pk_bf16_f32 v133, v138, v139
	global_store_dwordx4 v[134:135], v[124:127], off
	global_store_dwordx4 v[134:135], v[120:123], off offset:16
	global_store_dwordx4 v[142:143], v[130:133], off
	s_waitcnt vmcnt(4)
	s_nop 1
	v_mov_b32_e32 v130, v172
	v_mov_b32_e32 v131, v173
	v_mov_b32_e32 v132, v174
	v_mov_b32_e32 v133, v175
	s_nop 0
	s_waitcnt vmcnt(3)
	v_mov_b32_e32 v138, v176
	v_mov_b32_e32 v139, v177
	v_mov_b32_e32 v140, v178
	v_mov_b32_e32 v141, v179
	v_mul_f32_e32 v125, v125, v125
	v_fmac_f32_e32 v125, v124, v124
	v_fmac_f32_e32 v125, v126, v126
	v_fmac_f32_e32 v125, v127, v127
	v_fmac_f32_e32 v125, v120, v120
	v_fmac_f32_e32 v125, v121, v121
	v_fmac_f32_e32 v125, v122, v122
	v_fmac_f32_e32 v125, v123, v123
	v_pk_add_f32 v[116:117], v[116:117], v[130:131]
	s_nop 0
	v_mul_f32_e32 v120, v117, v117
	v_pk_add_f32 v[118:119], v[118:119], v[132:133]
	v_fmac_f32_e32 v120, v116, v116
	v_fmac_f32_e32 v120, v118, v118
	v_pk_add_f32 v[112:113], v[112:113], v[138:139]
	v_fmac_f32_e32 v120, v119, v119
	v_fmac_f32_e32 v120, v112, v112
	v_pk_add_f32 v[114:115], v[114:115], v[140:141]
	v_fmac_f32_e32 v120, v113, v113
	v_fmac_f32_e32 v120, v114, v114
	v_fmac_f32_e32 v120, v115, v115
	v_add_f32_e32 v124, v125, v120
	ds_bpermute_b32 v125, v137, v124
	global_store_dwordx4 v[134:135], v[116:119], off offset:512
	global_store_dwordx4 v[134:135], v[112:115], off offset:528
	v_pk_mul_f32 v[122:123], v[80:81], v[112:113]
	v_pk_mul_f32 v[118:119], v[86:87], v[118:119]
	v_pk_mul_f32 v[116:117], v[84:85], v[116:117]
	s_waitcnt lgkmcnt(0)
	v_add_f32_e32 v112, v124, v125
	ds_bpermute_b32 v113, v136, v112
	v_pk_mul_f32 v[120:121], v[82:83], v[114:115]
	v_cvt_pk_bf16_f32 v114, v116, v117
	v_cvt_pk_bf16_f32 v115, v118, v119
	v_cvt_pk_bf16_f32 v116, v122, v123
	v_cvt_pk_bf16_f32 v117, v120, v121
	global_store_dwordx4 v[142:143], v[114:117], off offset:256
	s_and_saveexec_b64 s[24:25], s[6:7]
	s_cbranch_execz .LBB0_786
	s_waitcnt lgkmcnt(0)
	v_add_f32_e32 v114, v112, v113
	v_lshl_add_u64 v[112:113], v[128:129], 2, s[12:13]
	global_atomic_add_f32 v[112:113], v114, off
.LBB0_786:
	s_or_b64 exec, exec, s[24:25]
	v_or_b32_e32 v112, 32, v162
	s_waitcnt lgkmcnt(0)
	v_ashrrev_i32_e32 v113, 31, v112
	v_lshlrev_b64 v[114:115], 13, v[112:113]
	v_lshl_add_u64 v[114:115], s[68:69], 0, v[114:115]
	v_lshl_add_u64 v[122:123], v[160:161], 2, v[114:115]
	global_load_dwordx4 v[114:117], v[122:123], off
	global_load_dwordx4 v[118:121], v[122:123], off offset:16
	global_load_dwordx4 v[172:175], v[122:123], off offset:512
	global_load_dwordx4 v[176:179], v[122:123], off offset:528
	v_lshlrev_b64 v[124:125], 12, v[112:113]
	v_lshl_add_u64 v[124:125], s[86:87], 0, v[124:125]
	v_lshl_add_u64 v[124:125], v[160:161], 1, v[124:125]
	s_waitcnt vmcnt(3)
	v_pk_add_f32 v[110:111], v[110:111], v[116:117]
	v_pk_add_f32 v[108:109], v[108:109], v[114:115]
	s_waitcnt vmcnt(2)
	v_pk_add_f32 v[106:107], v[106:107], v[120:121]
	v_pk_add_f32 v[104:105], v[104:105], v[118:119]
	v_pk_mul_f32 v[116:117], v[94:95], v[110:111]
	v_pk_mul_f32 v[114:115], v[92:93], v[108:109]
	v_pk_mul_f32 v[118:119], v[90:91], v[106:107]
	v_pk_mul_f32 v[120:121], v[88:89], v[104:105]
	v_cvt_pk_bf16_f32 v114, v114, v115
	v_cvt_pk_bf16_f32 v115, v116, v117
	v_cvt_pk_bf16_f32 v116, v120, v121
	v_cvt_pk_bf16_f32 v117, v118, v119
	global_store_dwordx4 v[122:123], v[108:111], off
	global_store_dwordx4 v[122:123], v[104:107], off offset:16
	global_store_dwordx4 v[124:125], v[114:117], off
	s_waitcnt vmcnt(4)
	s_nop 1
	v_mov_b32_e32 v114, v172
	v_mov_b32_e32 v115, v173
	v_mov_b32_e32 v116, v174
	v_mov_b32_e32 v117, v175
	s_nop 0
	s_waitcnt vmcnt(3)
	v_mov_b32_e32 v118, v176
	v_mov_b32_e32 v119, v177
	v_mov_b32_e32 v120, v178
	v_mov_b32_e32 v121, v179
	v_mul_f32_e32 v109, v109, v109
	v_fmac_f32_e32 v109, v108, v108
	v_fmac_f32_e32 v109, v110, v110
	v_fmac_f32_e32 v109, v111, v111
	v_fmac_f32_e32 v109, v104, v104
	v_fmac_f32_e32 v109, v105, v105
	v_fmac_f32_e32 v109, v106, v106
	v_fmac_f32_e32 v109, v107, v107
	v_pk_add_f32 v[100:101], v[100:101], v[114:115]
	s_nop 0
	v_mul_f32_e32 v104, v101, v101
	v_pk_add_f32 v[102:103], v[102:103], v[116:117]
	v_fmac_f32_e32 v104, v100, v100
	v_fmac_f32_e32 v104, v102, v102
	v_pk_add_f32 v[96:97], v[96:97], v[118:119]
	v_fmac_f32_e32 v104, v103, v103
	v_fmac_f32_e32 v104, v96, v96
	v_pk_add_f32 v[98:99], v[98:99], v[120:121]
	v_fmac_f32_e32 v104, v97, v97
	v_fmac_f32_e32 v104, v98, v98
	v_fmac_f32_e32 v104, v99, v99
	v_add_f32_e32 v108, v109, v104
	ds_bpermute_b32 v109, v137, v108
	global_store_dwordx4 v[122:123], v[100:103], off offset:512
	global_store_dwordx4 v[122:123], v[96:99], off offset:528
	v_pk_mul_f32 v[106:107], v[80:81], v[96:97]
	v_pk_mul_f32 v[102:103], v[86:87], v[102:103]
	v_pk_mul_f32 v[100:101], v[84:85], v[100:101]
	s_waitcnt lgkmcnt(0)
	v_add_f32_e32 v96, v108, v109
	ds_bpermute_b32 v97, v136, v96
	v_pk_mul_f32 v[104:105], v[82:83], v[98:99]
	v_cvt_pk_bf16_f32 v98, v100, v101
	v_cvt_pk_bf16_f32 v99, v102, v103
	v_cvt_pk_bf16_f32 v100, v106, v107
	v_cvt_pk_bf16_f32 v101, v104, v105
	global_store_dwordx4 v[124:125], v[98:101], off offset:256
	s_and_saveexec_b64 s[24:25], s[6:7]
	s_cbranch_execz .LBB0_788
	s_waitcnt lgkmcnt(0)
	v_add_f32_e32 v98, v96, v97
	v_lshl_add_u64 v[96:97], v[112:113], 2, s[12:13]
	global_atomic_add_f32 v[96:97], v98, off
; DI u32 pack2(float a, float b) { f32v2 v = {a, b}; return __builtin_bit_cast(u32, __builtin_convertvector(v, bf16v2)); }
;   DI void operator()(const f32x4 (&acc)[2][2][4][2], const Unit& u, int wr, int wc, int fr, int fq) const {
;     ...
;     for (int ai = 0; ai < 2; ++ai)
; #pragma unroll
;       for (int m = 0; m < 4; ++m) {
;         const int row = row0 + ai * HALF + m * 16;
;         float* dst = out + (size_t)row * DM + col0;
;         const float* src = layer == 0 ? (row < PROWS ? xp + (size_t)row * DM + col0 : xs + (size_t)(row - PROWS) * DM + col0) : dst;
;         float ss = 0.f;
; #pragma unroll
;         for (int bj = 0; bj < 2; ++bj) {
;           const f32x4 x0 = *reinterpret_cast<const f32x4*>(src + bj * HALF), x1 = *reinterpret_cast<const f32x4*>(src + bj * HALF + 4);
;           const f32x4 n0 = x0 + acc[ai][bj][m][0], n1 = x1 + acc[ai][bj][m][1];
;           *reinterpret_cast<f32x4*>(dst + bj * HALF) = n0; *reinterpret_cast<f32x4*>(dst + bj * HALF + 4) = n1;
;           ss += n0[0] * n0[0] + n0[1] * n0[1] + n0[2] * n0[2] + n0[3] * n0[3] + n1[0] * n1[0] + n1[1] * n1[1] + n1[2] * n1[2] + n1[3] * n1[3];
;           if (xw) {
;             const f32x4 h0 = n0 * wv[bj][0], h1 = n1 * wv[bj][1];
;             u32x4 pk = {pack2(h0[0], h0[1]), pack2(h0[2], h0[3]), pack2(h1[0], h1[1]), pack2(h1[2], h1[3])};
;             *reinterpret_cast<u32x4*>(xw + (size_t)row * DM + col0 + bj * HALF) = pk;
;           }
;         }
;         ss += __shfl_xor(ss, 16); ss += __shfl_xor(ss, 32);
;         if (fq == 0) atomicAdd(rs + row, ss);
;       }
.LBB0_788:
	s_or_b64 exec, exec, s[24:25]
	v_or_b32_e32 v96, 48, v162
	s_waitcnt lgkmcnt(0)
	v_ashrrev_i32_e32 v97, 31, v96
	v_lshlrev_b64 v[98:99], 13, v[96:97]
	v_lshl_add_u64 v[98:99], s[68:69], 0, v[98:99]
	v_lshl_add_u64 v[106:107], v[160:161], 2, v[98:99]
	global_load_dwordx4 v[98:101], v[106:107], off
	global_load_dwordx4 v[102:105], v[106:107], off offset:16
	global_load_dwordx4 v[172:175], v[106:107], off offset:512
	global_load_dwordx4 v[176:179], v[106:107], off offset:528
	v_lshlrev_b64 v[108:109], 12, v[96:97]
	v_lshl_add_u64 v[108:109], s[86:87], 0, v[108:109]
	v_lshl_add_u64 v[108:109], v[160:161], 1, v[108:109]
	s_waitcnt vmcnt(3)
	v_pk_add_f32 v[78:79], v[78:79], v[100:101]
	v_pk_add_f32 v[76:77], v[76:77], v[98:99]
	s_waitcnt vmcnt(2)
	v_pk_add_f32 v[74:75], v[74:75], v[104:105]
	v_pk_add_f32 v[72:73], v[72:73], v[102:103]
	v_pk_mul_f32 v[100:101], v[94:95], v[78:79]
	v_pk_mul_f32 v[98:99], v[92:93], v[76:77]
	v_pk_mul_f32 v[102:103], v[90:91], v[74:75]
	v_pk_mul_f32 v[104:105], v[88:89], v[72:73]
	v_cvt_pk_bf16_f32 v98, v98, v99
	v_cvt_pk_bf16_f32 v99, v100, v101
	v_cvt_pk_bf16_f32 v100, v104, v105
	v_cvt_pk_bf16_f32 v101, v102, v103
	global_store_dwordx4 v[106:107], v[76:79], off
	global_store_dwordx4 v[106:107], v[72:75], off offset:16
	global_store_dwordx4 v[108:109], v[98:101], off
	s_waitcnt vmcnt(4)
	s_nop 1
	v_mov_b32_e32 v98, v172
	v_mov_b32_e32 v99, v173
	v_mov_b32_e32 v100, v174
	v_mov_b32_e32 v101, v175
	s_nop 0
	s_waitcnt vmcnt(3)
	v_mov_b32_e32 v102, v176
	v_mov_b32_e32 v103, v177
	v_mov_b32_e32 v104, v178
	v_mov_b32_e32 v105, v179
	v_mul_f32_e32 v77, v77, v77
	v_fmac_f32_e32 v77, v76, v76
	v_fmac_f32_e32 v77, v78, v78
	v_fmac_f32_e32 v77, v79, v79
	v_fmac_f32_e32 v77, v72, v72
	v_fmac_f32_e32 v77, v73, v73
	v_fmac_f32_e32 v77, v74, v74
	v_fmac_f32_e32 v77, v75, v75
	v_pk_add_f32 v[68:69], v[68:69], v[98:99]
	s_nop 0
	v_mul_f32_e32 v72, v69, v69
	v_pk_add_f32 v[70:71], v[70:71], v[100:101]
	v_fmac_f32_e32 v72, v68, v68
	v_fmac_f32_e32 v72, v70, v70
	v_pk_add_f32 v[64:65], v[64:65], v[102:103]
	v_fmac_f32_e32 v72, v71, v71
	v_fmac_f32_e32 v72, v64, v64
	v_pk_add_f32 v[66:67], v[66:67], v[104:105]
	v_fmac_f32_e32 v72, v65, v65
	v_fmac_f32_e32 v72, v66, v66
	v_fmac_f32_e32 v72, v67, v67
	v_add_f32_e32 v76, v77, v72
	ds_bpermute_b32 v77, v137, v76
	global_store_dwordx4 v[106:107], v[68:71], off offset:512
	global_store_dwordx4 v[106:107], v[64:67], off offset:528
	v_pk_mul_f32 v[74:75], v[80:81], v[64:65]
	v_pk_mul_f32 v[70:71], v[86:87], v[70:71]
	v_pk_mul_f32 v[68:69], v[84:85], v[68:69]
	s_waitcnt lgkmcnt(0)
	v_add_f32_e32 v64, v76, v77
	ds_bpermute_b32 v65, v136, v64
	v_pk_mul_f32 v[72:73], v[82:83], v[66:67]
	v_cvt_pk_bf16_f32 v66, v68, v69
	v_cvt_pk_bf16_f32 v67, v70, v71
	v_cvt_pk_bf16_f32 v68, v74, v75
	v_cvt_pk_bf16_f32 v69, v72, v73
	global_store_dwordx4 v[108:109], v[66:69], off offset:256
	s_and_saveexec_b64 s[24:25], s[6:7]
	s_cbranch_execz .LBB0_790
	s_waitcnt lgkmcnt(0)
	v_add_f32_e32 v66, v64, v65
	v_lshl_add_u64 v[64:65], v[96:97], 2, s[12:13]
	global_atomic_add_f32 v[64:65], v66, off
.LBB0_790:
	s_or_b64 exec, exec, s[24:25]
	v_add_u32_e32 v64, 0x80, v162
	s_waitcnt lgkmcnt(0)
	v_ashrrev_i32_e32 v65, 31, v64
	v_lshlrev_b64 v[66:67], 13, v[64:65]
	v_lshl_add_u64 v[66:67], s[68:69], 0, v[66:67]
	v_lshl_add_u64 v[74:75], v[160:161], 2, v[66:67]
	global_load_dwordx4 v[66:69], v[74:75], off
	global_load_dwordx4 v[70:73], v[74:75], off offset:16
	global_load_dwordx4 v[172:175], v[74:75], off offset:512
	global_load_dwordx4 v[176:179], v[74:75], off offset:528
	v_lshlrev_b64 v[76:77], 12, v[64:65]
	v_lshl_add_u64 v[76:77], s[86:87], 0, v[76:77]
	v_lshl_add_u64 v[76:77], v[160:161], 1, v[76:77]
	s_waitcnt vmcnt(3)
	v_pk_add_f32 v[62:63], v[62:63], v[68:69]
	v_pk_add_f32 v[60:61], v[60:61], v[66:67]
	s_waitcnt vmcnt(2)
	v_pk_add_f32 v[58:59], v[58:59], v[72:73]
	v_pk_add_f32 v[56:57], v[56:57], v[70:71]
	v_pk_mul_f32 v[68:69], v[94:95], v[62:63]
	v_pk_mul_f32 v[66:67], v[92:93], v[60:61]
	v_pk_mul_f32 v[70:71], v[90:91], v[58:59]
	v_pk_mul_f32 v[72:73], v[88:89], v[56:57]
	v_cvt_pk_bf16_f32 v66, v66, v67
	v_cvt_pk_bf16_f32 v67, v68, v69
	v_cvt_pk_bf16_f32 v68, v72, v73
	v_cvt_pk_bf16_f32 v69, v70, v71
	global_store_dwordx4 v[74:75], v[60:63], off
	global_store_dwordx4 v[74:75], v[56:59], off offset:16
	global_store_dwordx4 v[76:77], v[66:69], off
	s_waitcnt vmcnt(4)
	s_nop 1
	v_mov_b32_e32 v66, v172
	v_mov_b32_e32 v67, v173
	v_mov_b32_e32 v68, v174
	v_mov_b32_e32 v69, v175
	s_nop 0
	s_waitcnt vmcnt(3)
	v_mov_b32_e32 v70, v176
	v_mov_b32_e32 v71, v177
	v_mov_b32_e32 v72, v178
	v_mov_b32_e32 v73, v179
	v_mul_f32_e32 v61, v61, v61
	v_fmac_f32_e32 v61, v60, v60
	v_fmac_f32_e32 v61, v62, v62
	v_fmac_f32_e32 v61, v63, v63
	v_fmac_f32_e32 v61, v56, v56
	v_fmac_f32_e32 v61, v57, v57
	v_fmac_f32_e32 v61, v58, v58
	v_fmac_f32_e32 v61, v59, v59
	v_pk_add_f32 v[52:53], v[52:53], v[66:67]
	s_nop 0
	v_mul_f32_e32 v56, v53, v53
	v_pk_add_f32 v[54:55], v[54:55], v[68:69]
	v_fmac_f32_e32 v56, v52, v52
	v_fmac_f32_e32 v56, v54, v54
	v_pk_add_f32 v[48:49], v[48:49], v[70:71]
	v_fmac_f32_e32 v56, v55, v55
	v_fmac_f32_e32 v56, v48, v48
	v_pk_add_f32 v[50:51], v[50:51], v[72:73]
	v_fmac_f32_e32 v56, v49, v49
	v_fmac_f32_e32 v56, v50, v50
	v_fmac_f32_e32 v56, v51, v51
	v_add_f32_e32 v60, v61, v56
	ds_bpermute_b32 v61, v137, v60
	global_store_dwordx4 v[74:75], v[52:55], off offset:512
	global_store_dwordx4 v[74:75], v[48:51], off offset:528
	v_pk_mul_f32 v[58:59], v[80:81], v[48:49]
	v_pk_mul_f32 v[54:55], v[86:87], v[54:55]
	v_pk_mul_f32 v[52:53], v[84:85], v[52:53]
	s_waitcnt lgkmcnt(0)
	v_add_f32_e32 v48, v60, v61
	ds_bpermute_b32 v49, v136, v48
	v_pk_mul_f32 v[56:57], v[82:83], v[50:51]
	v_cvt_pk_bf16_f32 v50, v52, v53
	v_cvt_pk_bf16_f32 v51, v54, v55
	v_cvt_pk_bf16_f32 v52, v58, v59
	v_cvt_pk_bf16_f32 v53, v56, v57
	global_store_dwordx4 v[76:77], v[50:53], off offset:256
	s_and_saveexec_b64 s[24:25], s[6:7]
	s_cbranch_execz .LBB0_792
	s_waitcnt lgkmcnt(0)
	v_add_f32_e32 v50, v48, v49
	v_lshl_add_u64 v[48:49], v[64:65], 2, s[12:13]
	global_atomic_add_f32 v[48:49], v50, off
; DI u32 pack2(float a, float b) { f32v2 v = {a, b}; return __builtin_bit_cast(u32, __builtin_convertvector(v, bf16v2)); }
;   DI void operator()(const f32x4 (&acc)[2][2][4][2], const Unit& u, int wr, int wc, int fr, int fq) const {
;     ...
;     for (int ai = 0; ai < 2; ++ai)
; #pragma unroll
;       for (int m = 0; m < 4; ++m) {
;         const int row = row0 + ai * HALF + m * 16;
;         float* dst = out + (size_t)row * DM + col0;
;         const float* src = layer == 0 ? (row < PROWS ? xp + (size_t)row * DM + col0 : xs + (size_t)(row - PROWS) * DM + col0) : dst;
;         float ss = 0.f;
; #pragma unroll
;         for (int bj = 0; bj < 2; ++bj) {
;           const f32x4 x0 = *reinterpret_cast<const f32x4*>(src + bj * HALF), x1 = *reinterpret_cast<const f32x4*>(src + bj * HALF + 4);
;           const f32x4 n0 = x0 + acc[ai][bj][m][0], n1 = x1 + acc[ai][bj][m][1];
;           *reinterpret_cast<f32x4*>(dst + bj * HALF) = n0; *reinterpret_cast<f32x4*>(dst + bj * HALF + 4) = n1;
;           ss += n0[0] * n0[0] + n0[1] * n0[1] + n0[2] * n0[2] + n0[3] * n0[3] + n1[0] * n1[0] + n1[1] * n1[1] + n1[2] * n1[2] + n1[3] * n1[3];
;           if (xw) {
;             const f32x4 h0 = n0 * wv[bj][0], h1 = n1 * wv[bj][1];
;             u32x4 pk = {pack2(h0[0], h0[1]), pack2(h0[2], h0[3]), pack2(h1[0], h1[1]), pack2(h1[2], h1[3])};
;             *reinterpret_cast<u32x4*>(xw + (size_t)row * DM + col0 + bj * HALF) = pk;
;           }
;         }
;         ss += __shfl_xor(ss, 16); ss += __shfl_xor(ss, 32);
;         if (fq == 0) atomicAdd(rs + row, ss);
;       }
.LBB0_792:
	s_or_b64 exec, exec, s[24:25]
	v_add_u32_e32 v48, 0x90, v162
	s_waitcnt lgkmcnt(0)
	v_ashrrev_i32_e32 v49, 31, v48
	v_lshlrev_b64 v[50:51], 13, v[48:49]
	v_lshl_add_u64 v[50:51], s[68:69], 0, v[50:51]
	v_lshl_add_u64 v[58:59], v[160:161], 2, v[50:51]
	global_load_dwordx4 v[50:53], v[58:59], off
	global_load_dwordx4 v[54:57], v[58:59], off offset:16
	global_load_dwordx4 v[172:175], v[58:59], off offset:512
	global_load_dwordx4 v[176:179], v[58:59], off offset:528
	v_lshlrev_b64 v[60:61], 12, v[48:49]
	v_lshl_add_u64 v[60:61], s[86:87], 0, v[60:61]
	v_lshl_add_u64 v[60:61], v[160:161], 1, v[60:61]
	s_waitcnt vmcnt(3)
	v_pk_add_f32 v[46:47], v[46:47], v[52:53]
	v_pk_add_f32 v[44:45], v[44:45], v[50:51]
	s_waitcnt vmcnt(2)
	v_pk_add_f32 v[42:43], v[42:43], v[56:57]
	v_pk_add_f32 v[40:41], v[40:41], v[54:55]
	v_pk_mul_f32 v[52:53], v[94:95], v[46:47]
	v_pk_mul_f32 v[50:51], v[92:93], v[44:45]
	v_pk_mul_f32 v[54:55], v[90:91], v[42:43]
	v_pk_mul_f32 v[56:57], v[88:89], v[40:41]
	v_cvt_pk_bf16_f32 v50, v50, v51
	v_cvt_pk_bf16_f32 v51, v52, v53
	v_cvt_pk_bf16_f32 v52, v56, v57
	v_cvt_pk_bf16_f32 v53, v54, v55
	global_store_dwordx4 v[58:59], v[44:47], off
	global_store_dwordx4 v[58:59], v[40:43], off offset:16
	global_store_dwordx4 v[60:61], v[50:53], off
	s_waitcnt vmcnt(4)
	s_nop 1
	v_mov_b32_e32 v50, v172
	v_mov_b32_e32 v51, v173
	v_mov_b32_e32 v52, v174
	v_mov_b32_e32 v53, v175
	s_nop 0
	s_waitcnt vmcnt(3)
	v_mov_b32_e32 v54, v176
	v_mov_b32_e32 v55, v177
	v_mov_b32_e32 v56, v178
	v_mov_b32_e32 v57, v179
	v_mul_f32_e32 v45, v45, v45
	v_fmac_f32_e32 v45, v44, v44
	v_fmac_f32_e32 v45, v46, v46
	v_fmac_f32_e32 v45, v47, v47
	v_fmac_f32_e32 v45, v40, v40
	v_fmac_f32_e32 v45, v41, v41
	v_fmac_f32_e32 v45, v42, v42
	v_fmac_f32_e32 v45, v43, v43
	v_pk_add_f32 v[36:37], v[36:37], v[50:51]
	s_nop 0
	v_mul_f32_e32 v40, v37, v37
	v_pk_add_f32 v[38:39], v[38:39], v[52:53]
	v_fmac_f32_e32 v40, v36, v36
	v_fmac_f32_e32 v40, v38, v38
	v_pk_add_f32 v[32:33], v[32:33], v[54:55]
	v_fmac_f32_e32 v40, v39, v39
	v_fmac_f32_e32 v40, v32, v32
	v_pk_add_f32 v[34:35], v[34:35], v[56:57]
	v_fmac_f32_e32 v40, v33, v33
	v_fmac_f32_e32 v40, v34, v34
	v_fmac_f32_e32 v40, v35, v35
	v_add_f32_e32 v44, v45, v40
	ds_bpermute_b32 v45, v137, v44
	global_store_dwordx4 v[58:59], v[36:39], off offset:512
	global_store_dwordx4 v[58:59], v[32:35], off offset:528
	v_pk_mul_f32 v[42:43], v[80:81], v[32:33]
	v_pk_mul_f32 v[38:39], v[86:87], v[38:39]
	v_pk_mul_f32 v[36:37], v[84:85], v[36:37]
	s_waitcnt lgkmcnt(0)
	v_add_f32_e32 v32, v44, v45
	ds_bpermute_b32 v33, v136, v32
	v_pk_mul_f32 v[40:41], v[82:83], v[34:35]
	v_cvt_pk_bf16_f32 v34, v36, v37
	v_cvt_pk_bf16_f32 v35, v38, v39
	v_cvt_pk_bf16_f32 v36, v42, v43
	v_cvt_pk_bf16_f32 v37, v40, v41
	global_store_dwordx4 v[60:61], v[34:37], off offset:256
	s_and_saveexec_b64 s[24:25], s[6:7]
	s_cbranch_execz .LBB0_794
	s_waitcnt lgkmcnt(0)
	v_add_f32_e32 v34, v32, v33
	v_lshl_add_u64 v[32:33], v[48:49], 2, s[12:13]
	global_atomic_add_f32 v[32:33], v34, off
; DI u32 pack2(float a, float b) { f32v2 v = {a, b}; return __builtin_bit_cast(u32, __builtin_convertvector(v, bf16v2)); }
;   DI void operator()(const f32x4 (&acc)[2][2][4][2], const Unit& u, int wr, int wc, int fr, int fq) const {
;     ...
;     for (int ai = 0; ai < 2; ++ai)
; #pragma unroll
;       for (int m = 0; m < 4; ++m) {
;         const int row = row0 + ai * HALF + m * 16;
;         float* dst = out + (size_t)row * DM + col0;
;         const float* src = layer == 0 ? (row < PROWS ? xp + (size_t)row * DM + col0 : xs + (size_t)(row - PROWS) * DM + col0) : dst;
;         float ss = 0.f;
; #pragma unroll
;         for (int bj = 0; bj < 2; ++bj) {
;           const f32x4 x0 = *reinterpret_cast<const f32x4*>(src + bj * HALF), x1 = *reinterpret_cast<const f32x4*>(src + bj * HALF + 4);
;           const f32x4 n0 = x0 + acc[ai][bj][m][0], n1 = x1 + acc[ai][bj][m][1];
;           *reinterpret_cast<f32x4*>(dst + bj * HALF) = n0; *reinterpret_cast<f32x4*>(dst + bj * HALF + 4) = n1;
;           ss += n0[0] * n0[0] + n0[1] * n0[1] + n0[2] * n0[2] + n0[3] * n0[3] + n1[0] * n1[0] + n1[1] * n1[1] + n1[2] * n1[2] + n1[3] * n1[3];
;           if (xw) {
;             const f32x4 h0 = n0 * wv[bj][0], h1 = n1 * wv[bj][1];
;             u32x4 pk = {pack2(h0[0], h0[1]), pack2(h0[2], h0[3]), pack2(h1[0], h1[1]), pack2(h1[2], h1[3])};
;             *reinterpret_cast<u32x4*>(xw + (size_t)row * DM + col0 + bj * HALF) = pk;
;           }
;         }
;         ss += __shfl_xor(ss, 16); ss += __shfl_xor(ss, 32);
;         if (fq == 0) atomicAdd(rs + row, ss);
;       }
.LBB0_794:
	s_or_b64 exec, exec, s[24:25]
	v_add_u32_e32 v32, 0xa0, v162
	s_waitcnt lgkmcnt(0)
	v_ashrrev_i32_e32 v33, 31, v32
	v_lshlrev_b64 v[34:35], 13, v[32:33]
	v_lshl_add_u64 v[34:35], s[68:69], 0, v[34:35]
	v_lshl_add_u64 v[42:43], v[160:161], 2, v[34:35]
	global_load_dwordx4 v[34:37], v[42:43], off
	global_load_dwordx4 v[38:41], v[42:43], off offset:16
	global_load_dwordx4 v[172:175], v[42:43], off offset:512
	global_load_dwordx4 v[176:179], v[42:43], off offset:528
	v_lshlrev_b64 v[44:45], 12, v[32:33]
	v_lshl_add_u64 v[44:45], s[86:87], 0, v[44:45]
	v_lshl_add_u64 v[44:45], v[160:161], 1, v[44:45]
	s_waitcnt vmcnt(3)
	v_pk_add_f32 v[30:31], v[30:31], v[36:37]
	v_pk_add_f32 v[28:29], v[28:29], v[34:35]
	s_waitcnt vmcnt(2)
	v_pk_add_f32 v[26:27], v[26:27], v[40:41]
	v_pk_add_f32 v[24:25], v[24:25], v[38:39]
	v_pk_mul_f32 v[36:37], v[94:95], v[30:31]
	v_pk_mul_f32 v[34:35], v[92:93], v[28:29]
	v_pk_mul_f32 v[38:39], v[90:91], v[26:27]
	v_pk_mul_f32 v[40:41], v[88:89], v[24:25]
	v_cvt_pk_bf16_f32 v34, v34, v35
	v_cvt_pk_bf16_f32 v35, v36, v37
	v_cvt_pk_bf16_f32 v36, v40, v41
	v_cvt_pk_bf16_f32 v37, v38, v39
	global_store_dwordx4 v[42:43], v[28:31], off
	global_store_dwordx4 v[42:43], v[24:27], off offset:16
	global_store_dwordx4 v[44:45], v[34:37], off
	s_waitcnt vmcnt(4)
	s_nop 1
	v_mov_b32_e32 v34, v172
	v_mov_b32_e32 v35, v173
	v_mov_b32_e32 v36, v174
	v_mov_b32_e32 v37, v175
	s_nop 0
	s_waitcnt vmcnt(3)
	v_mov_b32_e32 v38, v176
	v_mov_b32_e32 v39, v177
	v_mov_b32_e32 v40, v178
	v_mov_b32_e32 v41, v179
	v_mul_f32_e32 v29, v29, v29
	v_fmac_f32_e32 v29, v28, v28
	v_fmac_f32_e32 v29, v30, v30
	v_fmac_f32_e32 v29, v31, v31
	v_fmac_f32_e32 v29, v24, v24
	v_fmac_f32_e32 v29, v25, v25
	v_fmac_f32_e32 v29, v26, v26
	v_fmac_f32_e32 v29, v27, v27
	v_pk_add_f32 v[20:21], v[20:21], v[34:35]
	s_nop 0
	v_mul_f32_e32 v24, v21, v21
	v_pk_add_f32 v[22:23], v[22:23], v[36:37]
	v_fmac_f32_e32 v24, v20, v20
	v_fmac_f32_e32 v24, v22, v22
	v_pk_add_f32 v[16:17], v[16:17], v[38:39]
	v_fmac_f32_e32 v24, v23, v23
	v_fmac_f32_e32 v24, v16, v16
	v_pk_add_f32 v[18:19], v[18:19], v[40:41]
	v_fmac_f32_e32 v24, v17, v17
	v_fmac_f32_e32 v24, v18, v18
	v_fmac_f32_e32 v24, v19, v19
	v_add_f32_e32 v28, v29, v24
	ds_bpermute_b32 v29, v137, v28
	global_store_dwordx4 v[42:43], v[20:23], off offset:512
	global_store_dwordx4 v[42:43], v[16:19], off offset:528
	v_pk_mul_f32 v[26:27], v[80:81], v[16:17]
	v_pk_mul_f32 v[22:23], v[86:87], v[22:23]
	v_pk_mul_f32 v[20:21], v[84:85], v[20:21]
	s_waitcnt lgkmcnt(0)
	v_add_f32_e32 v16, v28, v29
	ds_bpermute_b32 v17, v136, v16
	v_pk_mul_f32 v[24:25], v[82:83], v[18:19]
	v_cvt_pk_bf16_f32 v18, v20, v21
	v_cvt_pk_bf16_f32 v19, v22, v23
	v_cvt_pk_bf16_f32 v20, v26, v27
	v_cvt_pk_bf16_f32 v21, v24, v25
	global_store_dwordx4 v[44:45], v[18:21], off offset:256
	s_and_saveexec_b64 s[24:25], s[6:7]
	s_cbranch_execz .LBB0_796
	s_waitcnt lgkmcnt(0)
	v_add_f32_e32 v18, v16, v17
	v_lshl_add_u64 v[16:17], v[32:33], 2, s[12:13]
	global_atomic_add_f32 v[16:17], v18, off
.LBB0_796:
	s_or_b64 exec, exec, s[24:25]
	v_add_u32_e32 v16, 0xb0, v162
	s_waitcnt lgkmcnt(0)
	v_ashrrev_i32_e32 v17, 31, v16
	v_lshlrev_b64 v[18:19], 13, v[16:17]
	v_lshl_add_u64 v[18:19], s[68:69], 0, v[18:19]
	v_lshl_add_u64 v[26:27], v[160:161], 2, v[18:19]
	global_load_dwordx4 v[18:21], v[26:27], off
	global_load_dwordx4 v[22:25], v[26:27], off offset:16
	global_load_dwordx4 v[172:175], v[26:27], off offset:512
	global_load_dwordx4 v[176:179], v[26:27], off offset:528
	v_lshlrev_b64 v[28:29], 12, v[16:17]
	v_lshl_add_u64 v[28:29], s[86:87], 0, v[28:29]
	v_lshl_add_u64 v[28:29], v[160:161], 1, v[28:29]
	s_waitcnt vmcnt(3)
	v_pk_add_f32 v[14:15], v[14:15], v[20:21]
	v_pk_add_f32 v[12:13], v[12:13], v[18:19]
	s_waitcnt vmcnt(2)
	v_pk_add_f32 v[10:11], v[10:11], v[24:25]
	v_pk_add_f32 v[8:9], v[8:9], v[22:23]
	v_pk_mul_f32 v[20:21], v[94:95], v[14:15]
	v_pk_mul_f32 v[18:19], v[92:93], v[12:13]
	v_pk_mul_f32 v[22:23], v[90:91], v[10:11]
	v_pk_mul_f32 v[24:25], v[88:89], v[8:9]
	v_cvt_pk_bf16_f32 v18, v18, v19
	v_cvt_pk_bf16_f32 v19, v20, v21
	v_cvt_pk_bf16_f32 v20, v24, v25
	v_cvt_pk_bf16_f32 v21, v22, v23
	global_store_dwordx4 v[26:27], v[12:15], off
	global_store_dwordx4 v[26:27], v[8:11], off offset:16
	global_store_dwordx4 v[28:29], v[18:21], off
	s_waitcnt vmcnt(4)
	s_nop 1
	v_mov_b32_e32 v18, v172
	v_mov_b32_e32 v19, v173
	v_mov_b32_e32 v20, v174
	v_mov_b32_e32 v21, v175
	s_nop 0
	s_waitcnt vmcnt(3)
	v_mov_b32_e32 v22, v176
	v_mov_b32_e32 v23, v177
	v_mov_b32_e32 v24, v178
	v_mov_b32_e32 v25, v179
	v_mul_f32_e32 v13, v13, v13
	v_fmac_f32_e32 v13, v12, v12
	v_fmac_f32_e32 v13, v14, v14
	v_fmac_f32_e32 v13, v15, v15
	v_fmac_f32_e32 v13, v8, v8
	v_fmac_f32_e32 v13, v9, v9
	v_fmac_f32_e32 v13, v10, v10
	v_fmac_f32_e32 v13, v11, v11
	v_pk_add_f32 v[4:5], v[4:5], v[18:19]
	s_nop 0
	v_mul_f32_e32 v8, v5, v5
	v_pk_add_f32 v[6:7], v[6:7], v[20:21]
	v_fmac_f32_e32 v8, v4, v4
	v_fmac_f32_e32 v8, v6, v6
	v_pk_add_f32 v[0:1], v[0:1], v[22:23]
	v_fmac_f32_e32 v8, v7, v7
	v_fmac_f32_e32 v8, v0, v0
	v_pk_add_f32 v[2:3], v[2:3], v[24:25]
	v_fmac_f32_e32 v8, v1, v1
	v_fmac_f32_e32 v8, v2, v2
	v_fmac_f32_e32 v8, v3, v3
	v_add_f32_e32 v12, v13, v8
	ds_bpermute_b32 v13, v137, v12
	global_store_dwordx4 v[26:27], v[4:7], off offset:512
	global_store_dwordx4 v[26:27], v[0:3], off offset:528
	v_pk_mul_f32 v[10:11], v[80:81], v[0:1]
	v_pk_mul_f32 v[6:7], v[86:87], v[6:7]
	v_pk_mul_f32 v[4:5], v[84:85], v[4:5]
	s_waitcnt lgkmcnt(0)
	v_add_f32_e32 v0, v12, v13
	ds_bpermute_b32 v1, v136, v0
	v_pk_mul_f32 v[8:9], v[82:83], v[2:3]
	v_cvt_pk_bf16_f32 v2, v4, v5
	v_cvt_pk_bf16_f32 v3, v6, v7
	v_cvt_pk_bf16_f32 v4, v10, v11
	v_cvt_pk_bf16_f32 v5, v8, v9
	global_store_dwordx4 v[28:29], v[2:5], off offset:256
	s_and_saveexec_b64 s[24:25], s[6:7]
	s_cbranch_execz .LBB0_777
	s_waitcnt lgkmcnt(0)
	v_add_f32_e32 v2, v0, v1
	v_lshl_add_u64 v[0:1], v[16:17], 2, s[12:13]
	global_atomic_add_f32 v[0:1], v2, off
	s_branch .LBB0_777

; DI u32 pack2(float a, float b) { f32v2 v = {a, b}; return __builtin_bit_cast(u32, __builtin_convertvector(v, bf16v2)); }
;   DI void operator()(const f32x4 (&acc)[2][2][4][2], const Unit& u, int wr, int wc, int fr, int fq) const {
;     ...
;     for (int ai = 0; ai < 2; ++ai)
; #pragma unroll
;       for (int m = 0; m < 4; ++m) {
;         const int row = row0 + ai * HALF + m * 16;
;         float* dst = out + (size_t)row * DM + col0;
;         const float* src = layer == 0 ? (row < PROWS ? xp + (size_t)row * DM + col0 : xs + (size_t)(row - PROWS) * DM + col0) : dst;
;         float ss = 0.f;
; #pragma unroll
;         for (int bj = 0; bj < 2; ++bj) {
;           const f32x4 x0 = *reinterpret_cast<const f32x4*>(src + bj * HALF), x1 = *reinterpret_cast<const f32x4*>(src + bj * HALF + 4);
;           const f32x4 n0 = x0 + acc[ai][bj][m][0], n1 = x1 + acc[ai][bj][m][1];
;           *reinterpret_cast<f32x4*>(dst + bj * HALF) = n0; *reinterpret_cast<f32x4*>(dst + bj * HALF + 4) = n1;
;           ss += n0[0] * n0[0] + n0[1] * n0[1] + n0[2] * n0[2] + n0[3] * n0[3] + n1[0] * n1[0] + n1[1] * n1[1] + n1[2] * n1[2] + n1[3] * n1[3];
;           if (xw) {
;             const f32x4 h0 = n0 * wv[bj][0], h1 = n1 * wv[bj][1];
;             u32x4 pk = {pack2(h0[0], h0[1]), pack2(h0[2], h0[3]), pack2(h1[0], h1[1]), pack2(h1[2], h1[3])};
;             *reinterpret_cast<u32x4*>(xw + (size_t)row * DM + col0 + bj * HALF) = pk;
;           }
;         }
;         ss += __shfl_xor(ss, 16); ss += __shfl_xor(ss, 32);
;         if (fq == 0) atomicAdd(rs + row, ss);
;       }
.LBB0_1143:
	s_or_b64 exec, exec, s[26:27]
	v_or_b32_e32 v128, 16, v162
	s_waitcnt lgkmcnt(0)
	v_ashrrev_i32_e32 v129, 31, v128
	v_lshlrev_b64 v[130:131], 13, v[128:129]
	v_lshl_add_u64 v[130:131], s[44:45], 0, v[130:131]
	v_lshl_add_u64 v[134:135], v[160:161], 2, v[130:131]
	global_load_dwordx4 v[130:133], v[134:135], off
	global_load_dwordx4 v[138:141], v[134:135], off offset:16
	global_load_dwordx4 v[172:175], v[134:135], off offset:512
	global_load_dwordx4 v[176:179], v[134:135], off offset:528
	v_lshlrev_b64 v[142:143], 12, v[128:129]
	v_lshl_add_u64 v[142:143], s[52:53], 0, v[142:143]
	v_lshl_add_u64 v[142:143], v[160:161], 1, v[142:143]
	s_waitcnt vmcnt(3)
	v_pk_add_f32 v[126:127], v[126:127], v[132:133]
	v_pk_add_f32 v[124:125], v[124:125], v[130:131]
	s_waitcnt vmcnt(2)
	v_pk_add_f32 v[122:123], v[122:123], v[140:141]
	v_pk_add_f32 v[120:121], v[120:121], v[138:139]
	v_pk_mul_f32 v[132:133], v[94:95], v[126:127]
	v_pk_mul_f32 v[130:131], v[92:93], v[124:125]
	v_pk_mul_f32 v[138:139], v[90:91], v[122:123]
	v_pk_mul_f32 v[140:141], v[88:89], v[120:121]
	v_cvt_pk_bf16_f32 v130, v130, v131
	v_cvt_pk_bf16_f32 v131, v132, v133
	v_cvt_pk_bf16_f32 v132, v140, v141
	v_cvt_pk_bf16_f32 v133, v138, v139
	global_store_dwordx4 v[134:135], v[124:127], off
	global_store_dwordx4 v[134:135], v[120:123], off offset:16
	global_store_dwordx4 v[142:143], v[130:133], off
	s_waitcnt vmcnt(4)
	s_nop 1
	v_mov_b32_e32 v130, v172
	v_mov_b32_e32 v131, v173
	v_mov_b32_e32 v132, v174
	v_mov_b32_e32 v133, v175
	s_nop 0
	s_waitcnt vmcnt(3)
	v_mov_b32_e32 v138, v176
	v_mov_b32_e32 v139, v177
	v_mov_b32_e32 v140, v178
	v_mov_b32_e32 v141, v179
	v_mul_f32_e32 v125, v125, v125
	v_fmac_f32_e32 v125, v124, v124
	v_fmac_f32_e32 v125, v126, v126
	v_fmac_f32_e32 v125, v127, v127
	v_fmac_f32_e32 v125, v120, v120
	v_fmac_f32_e32 v125, v121, v121
	v_fmac_f32_e32 v125, v122, v122
	v_fmac_f32_e32 v125, v123, v123
	v_pk_add_f32 v[116:117], v[116:117], v[130:131]
	s_nop 0
	v_mul_f32_e32 v120, v117, v117
	v_pk_add_f32 v[118:119], v[118:119], v[132:133]
	v_fmac_f32_e32 v120, v116, v116
	v_fmac_f32_e32 v120, v118, v118
	v_pk_add_f32 v[112:113], v[112:113], v[138:139]
	v_fmac_f32_e32 v120, v119, v119
	v_fmac_f32_e32 v120, v112, v112
	v_pk_add_f32 v[114:115], v[114:115], v[140:141]
	v_fmac_f32_e32 v120, v113, v113
	v_fmac_f32_e32 v120, v114, v114
	v_fmac_f32_e32 v120, v115, v115
	v_add_f32_e32 v124, v125, v120
	ds_bpermute_b32 v125, v137, v124
	global_store_dwordx4 v[134:135], v[116:119], off offset:512
	global_store_dwordx4 v[134:135], v[112:115], off offset:528
	v_pk_mul_f32 v[122:123], v[80:81], v[112:113]
	v_pk_mul_f32 v[118:119], v[86:87], v[118:119]
	v_pk_mul_f32 v[116:117], v[84:85], v[116:117]
	s_waitcnt lgkmcnt(0)
	v_add_f32_e32 v112, v124, v125
	ds_bpermute_b32 v113, v136, v112
	v_pk_mul_f32 v[120:121], v[82:83], v[114:115]
	v_cvt_pk_bf16_f32 v114, v116, v117
	v_cvt_pk_bf16_f32 v115, v118, v119
	v_cvt_pk_bf16_f32 v116, v122, v123
	v_cvt_pk_bf16_f32 v117, v120, v121
	global_store_dwordx4 v[142:143], v[114:117], off offset:256
	s_and_saveexec_b64 s[26:27], s[8:9]
	s_cbranch_execz .LBB0_1145
	s_waitcnt lgkmcnt(0)
	v_add_f32_e32 v114, v112, v113
	v_lshl_add_u64 v[112:113], v[128:129], 2, s[14:15]
	global_atomic_add_f32 v[112:113], v114, off
.LBB0_1145:
	s_or_b64 exec, exec, s[26:27]
	v_or_b32_e32 v112, 32, v162
	s_waitcnt lgkmcnt(0)
	v_ashrrev_i32_e32 v113, 31, v112
	v_lshlrev_b64 v[114:115], 13, v[112:113]
	v_lshl_add_u64 v[114:115], s[44:45], 0, v[114:115]
	v_lshl_add_u64 v[122:123], v[160:161], 2, v[114:115]
	global_load_dwordx4 v[114:117], v[122:123], off
	global_load_dwordx4 v[118:121], v[122:123], off offset:16
	global_load_dwordx4 v[172:175], v[122:123], off offset:512
	global_load_dwordx4 v[176:179], v[122:123], off offset:528
	v_lshlrev_b64 v[124:125], 12, v[112:113]
	v_lshl_add_u64 v[124:125], s[52:53], 0, v[124:125]
	v_lshl_add_u64 v[124:125], v[160:161], 1, v[124:125]
	s_waitcnt vmcnt(3)
	v_pk_add_f32 v[110:111], v[110:111], v[116:117]
	v_pk_add_f32 v[108:109], v[108:109], v[114:115]
	s_waitcnt vmcnt(2)
	v_pk_add_f32 v[106:107], v[106:107], v[120:121]
	v_pk_add_f32 v[104:105], v[104:105], v[118:119]
	v_pk_mul_f32 v[116:117], v[94:95], v[110:111]
	v_pk_mul_f32 v[114:115], v[92:93], v[108:109]
	v_pk_mul_f32 v[118:119], v[90:91], v[106:107]
	v_pk_mul_f32 v[120:121], v[88:89], v[104:105]
	v_cvt_pk_bf16_f32 v114, v114, v115
	v_cvt_pk_bf16_f32 v115, v116, v117
	v_cvt_pk_bf16_f32 v116, v120, v121
	v_cvt_pk_bf16_f32 v117, v118, v119
	global_store_dwordx4 v[122:123], v[108:111], off
	global_store_dwordx4 v[122:123], v[104:107], off offset:16
	global_store_dwordx4 v[124:125], v[114:117], off
	s_waitcnt vmcnt(4)
	s_nop 1
	v_mov_b32_e32 v114, v172
	v_mov_b32_e32 v115, v173
	v_mov_b32_e32 v116, v174
	v_mov_b32_e32 v117, v175
	s_nop 0
	s_waitcnt vmcnt(3)
	v_mov_b32_e32 v118, v176
	v_mov_b32_e32 v119, v177
	v_mov_b32_e32 v120, v178
	v_mov_b32_e32 v121, v179
	v_mul_f32_e32 v109, v109, v109
	v_fmac_f32_e32 v109, v108, v108
	v_fmac_f32_e32 v109, v110, v110
	v_fmac_f32_e32 v109, v111, v111
	v_fmac_f32_e32 v109, v104, v104
	v_fmac_f32_e32 v109, v105, v105
	v_fmac_f32_e32 v109, v106, v106
	v_fmac_f32_e32 v109, v107, v107
	v_pk_add_f32 v[100:101], v[100:101], v[114:115]
	s_nop 0
	v_mul_f32_e32 v104, v101, v101
	v_pk_add_f32 v[102:103], v[102:103], v[116:117]
	v_fmac_f32_e32 v104, v100, v100
	v_fmac_f32_e32 v104, v102, v102
	v_pk_add_f32 v[96:97], v[96:97], v[118:119]
	v_fmac_f32_e32 v104, v103, v103
	v_fmac_f32_e32 v104, v96, v96
	v_pk_add_f32 v[98:99], v[98:99], v[120:121]
	v_fmac_f32_e32 v104, v97, v97
	v_fmac_f32_e32 v104, v98, v98
	v_fmac_f32_e32 v104, v99, v99
	v_add_f32_e32 v108, v109, v104
	ds_bpermute_b32 v109, v137, v108
	global_store_dwordx4 v[122:123], v[100:103], off offset:512
	global_store_dwordx4 v[122:123], v[96:99], off offset:528
	v_pk_mul_f32 v[106:107], v[80:81], v[96:97]
	v_pk_mul_f32 v[102:103], v[86:87], v[102:103]
	v_pk_mul_f32 v[100:101], v[84:85], v[100:101]
	s_waitcnt lgkmcnt(0)
	v_add_f32_e32 v96, v108, v109
	ds_bpermute_b32 v97, v136, v96
	v_pk_mul_f32 v[104:105], v[82:83], v[98:99]
	v_cvt_pk_bf16_f32 v98, v100, v101
	v_cvt_pk_bf16_f32 v99, v102, v103
	v_cvt_pk_bf16_f32 v100, v106, v107
	v_cvt_pk_bf16_f32 v101, v104, v105
	global_store_dwordx4 v[124:125], v[98:101], off offset:256
	s_and_saveexec_b64 s[26:27], s[8:9]
	s_cbranch_execz .LBB0_1147
	s_waitcnt lgkmcnt(0)
	v_add_f32_e32 v98, v96, v97
	v_lshl_add_u64 v[96:97], v[112:113], 2, s[14:15]
	global_atomic_add_f32 v[96:97], v98, off
; DI u32 pack2(float a, float b) { f32v2 v = {a, b}; return __builtin_bit_cast(u32, __builtin_convertvector(v, bf16v2)); }
;   DI void operator()(const f32x4 (&acc)[2][2][4][2], const Unit& u, int wr, int wc, int fr, int fq) const {
;     ...
;     for (int ai = 0; ai < 2; ++ai)
; #pragma unroll
;       for (int m = 0; m < 4; ++m) {
;         const int row = row0 + ai * HALF + m * 16;
;         float* dst = out + (size_t)row * DM + col0;
;         const float* src = layer == 0 ? (row < PROWS ? xp + (size_t)row * DM + col0 : xs + (size_t)(row - PROWS) * DM + col0) : dst;
;         float ss = 0.f;
; #pragma unroll
;         for (int bj = 0; bj < 2; ++bj) {
;           const f32x4 x0 = *reinterpret_cast<const f32x4*>(src + bj * HALF), x1 = *reinterpret_cast<const f32x4*>(src + bj * HALF + 4);
;           const f32x4 n0 = x0 + acc[ai][bj][m][0], n1 = x1 + acc[ai][bj][m][1];
;           *reinterpret_cast<f32x4*>(dst + bj * HALF) = n0; *reinterpret_cast<f32x4*>(dst + bj * HALF + 4) = n1;
;           ss += n0[0] * n0[0] + n0[1] * n0[1] + n0[2] * n0[2] + n0[3] * n0[3] + n1[0] * n1[0] + n1[1] * n1[1] + n1[2] * n1[2] + n1[3] * n1[3];
;           if (xw) {
;             const f32x4 h0 = n0 * wv[bj][0], h1 = n1 * wv[bj][1];
;             u32x4 pk = {pack2(h0[0], h0[1]), pack2(h0[2], h0[3]), pack2(h1[0], h1[1]), pack2(h1[2], h1[3])};
;             *reinterpret_cast<u32x4*>(xw + (size_t)row * DM + col0 + bj * HALF) = pk;
;           }
;         }
;         ss += __shfl_xor(ss, 16); ss += __shfl_xor(ss, 32);
;         if (fq == 0) atomicAdd(rs + row, ss);
;       }
.LBB0_1147:
	s_or_b64 exec, exec, s[26:27]
	v_or_b32_e32 v96, 48, v162
	s_waitcnt lgkmcnt(0)
	v_ashrrev_i32_e32 v97, 31, v96
	v_lshlrev_b64 v[98:99], 13, v[96:97]
	v_lshl_add_u64 v[98:99], s[44:45], 0, v[98:99]
	v_lshl_add_u64 v[106:107], v[160:161], 2, v[98:99]
	global_load_dwordx4 v[98:101], v[106:107], off
	global_load_dwordx4 v[102:105], v[106:107], off offset:16
	global_load_dwordx4 v[172:175], v[106:107], off offset:512
	global_load_dwordx4 v[176:179], v[106:107], off offset:528
	v_lshlrev_b64 v[108:109], 12, v[96:97]
	v_lshl_add_u64 v[108:109], s[52:53], 0, v[108:109]
	v_lshl_add_u64 v[108:109], v[160:161], 1, v[108:109]
	s_waitcnt vmcnt(3)
	v_pk_add_f32 v[78:79], v[78:79], v[100:101]
	v_pk_add_f32 v[76:77], v[76:77], v[98:99]
	s_waitcnt vmcnt(2)
	v_pk_add_f32 v[74:75], v[74:75], v[104:105]
	v_pk_add_f32 v[72:73], v[72:73], v[102:103]
	v_pk_mul_f32 v[100:101], v[94:95], v[78:79]
	v_pk_mul_f32 v[98:99], v[92:93], v[76:77]
	v_pk_mul_f32 v[102:103], v[90:91], v[74:75]
	v_pk_mul_f32 v[104:105], v[88:89], v[72:73]
	v_cvt_pk_bf16_f32 v98, v98, v99
	v_cvt_pk_bf16_f32 v99, v100, v101
	v_cvt_pk_bf16_f32 v100, v104, v105
	v_cvt_pk_bf16_f32 v101, v102, v103
	global_store_dwordx4 v[106:107], v[76:79], off
	global_store_dwordx4 v[106:107], v[72:75], off offset:16
	global_store_dwordx4 v[108:109], v[98:101], off
	s_waitcnt vmcnt(4)
	s_nop 1
	v_mov_b32_e32 v98, v172
	v_mov_b32_e32 v99, v173
	v_mov_b32_e32 v100, v174
	v_mov_b32_e32 v101, v175
	s_nop 0
	s_waitcnt vmcnt(3)
	v_mov_b32_e32 v102, v176
	v_mov_b32_e32 v103, v177
	v_mov_b32_e32 v104, v178
	v_mov_b32_e32 v105, v179
	v_mul_f32_e32 v77, v77, v77
	v_fmac_f32_e32 v77, v76, v76
	v_fmac_f32_e32 v77, v78, v78
	v_fmac_f32_e32 v77, v79, v79
	v_fmac_f32_e32 v77, v72, v72
	v_fmac_f32_e32 v77, v73, v73
	v_fmac_f32_e32 v77, v74, v74
	v_fmac_f32_e32 v77, v75, v75
	v_pk_add_f32 v[68:69], v[68:69], v[98:99]
	s_nop 0
	v_mul_f32_e32 v72, v69, v69
	v_pk_add_f32 v[70:71], v[70:71], v[100:101]
	v_fmac_f32_e32 v72, v68, v68
	v_fmac_f32_e32 v72, v70, v70
	v_pk_add_f32 v[64:65], v[64:65], v[102:103]
	v_fmac_f32_e32 v72, v71, v71
	v_fmac_f32_e32 v72, v64, v64
	v_pk_add_f32 v[66:67], v[66:67], v[104:105]
	v_fmac_f32_e32 v72, v65, v65
	v_fmac_f32_e32 v72, v66, v66
	v_fmac_f32_e32 v72, v67, v67
	v_add_f32_e32 v76, v77, v72
	ds_bpermute_b32 v77, v137, v76
	global_store_dwordx4 v[106:107], v[68:71], off offset:512
	global_store_dwordx4 v[106:107], v[64:67], off offset:528
	v_pk_mul_f32 v[74:75], v[80:81], v[64:65]
	v_pk_mul_f32 v[70:71], v[86:87], v[70:71]
	v_pk_mul_f32 v[68:69], v[84:85], v[68:69]
	s_waitcnt lgkmcnt(0)
	v_add_f32_e32 v64, v76, v77
	ds_bpermute_b32 v65, v136, v64
	v_pk_mul_f32 v[72:73], v[82:83], v[66:67]
	v_cvt_pk_bf16_f32 v66, v68, v69
	v_cvt_pk_bf16_f32 v67, v70, v71
	v_cvt_pk_bf16_f32 v68, v74, v75
	v_cvt_pk_bf16_f32 v69, v72, v73
	global_store_dwordx4 v[108:109], v[66:69], off offset:256
	s_and_saveexec_b64 s[26:27], s[8:9]
	s_cbranch_execz .LBB0_1149
	s_waitcnt lgkmcnt(0)
	v_add_f32_e32 v66, v64, v65
	v_lshl_add_u64 v[64:65], v[96:97], 2, s[14:15]
	global_atomic_add_f32 v[64:65], v66, off
.LBB0_1149:
	s_or_b64 exec, exec, s[26:27]
	v_add_u32_e32 v64, 0x80, v162
	s_waitcnt lgkmcnt(0)
	v_ashrrev_i32_e32 v65, 31, v64
	v_lshlrev_b64 v[66:67], 13, v[64:65]
	v_lshl_add_u64 v[66:67], s[44:45], 0, v[66:67]
	v_lshl_add_u64 v[74:75], v[160:161], 2, v[66:67]
	global_load_dwordx4 v[66:69], v[74:75], off
	global_load_dwordx4 v[70:73], v[74:75], off offset:16
	global_load_dwordx4 v[172:175], v[74:75], off offset:512
	global_load_dwordx4 v[176:179], v[74:75], off offset:528
	v_lshlrev_b64 v[76:77], 12, v[64:65]
	v_lshl_add_u64 v[76:77], s[52:53], 0, v[76:77]
	v_lshl_add_u64 v[76:77], v[160:161], 1, v[76:77]
	s_waitcnt vmcnt(3)
	v_pk_add_f32 v[62:63], v[62:63], v[68:69]
	v_pk_add_f32 v[60:61], v[60:61], v[66:67]
	s_waitcnt vmcnt(2)
	v_pk_add_f32 v[58:59], v[58:59], v[72:73]
	v_pk_add_f32 v[56:57], v[56:57], v[70:71]
	v_pk_mul_f32 v[68:69], v[94:95], v[62:63]
	v_pk_mul_f32 v[66:67], v[92:93], v[60:61]
	v_pk_mul_f32 v[70:71], v[90:91], v[58:59]
	v_pk_mul_f32 v[72:73], v[88:89], v[56:57]
	v_cvt_pk_bf16_f32 v66, v66, v67
	v_cvt_pk_bf16_f32 v67, v68, v69
	v_cvt_pk_bf16_f32 v68, v72, v73
	v_cvt_pk_bf16_f32 v69, v70, v71
	global_store_dwordx4 v[74:75], v[60:63], off
	global_store_dwordx4 v[74:75], v[56:59], off offset:16
	global_store_dwordx4 v[76:77], v[66:69], off
	s_waitcnt vmcnt(4)
	s_nop 1
	v_mov_b32_e32 v66, v172
	v_mov_b32_e32 v67, v173
	v_mov_b32_e32 v68, v174
	v_mov_b32_e32 v69, v175
	s_nop 0
	s_waitcnt vmcnt(3)
	v_mov_b32_e32 v70, v176
	v_mov_b32_e32 v71, v177
	v_mov_b32_e32 v72, v178
	v_mov_b32_e32 v73, v179
	v_mul_f32_e32 v61, v61, v61
	v_fmac_f32_e32 v61, v60, v60
	v_fmac_f32_e32 v61, v62, v62
	v_fmac_f32_e32 v61, v63, v63
	v_fmac_f32_e32 v61, v56, v56
	v_fmac_f32_e32 v61, v57, v57
	v_fmac_f32_e32 v61, v58, v58
	v_fmac_f32_e32 v61, v59, v59
	v_pk_add_f32 v[52:53], v[52:53], v[66:67]
	s_nop 0
	v_mul_f32_e32 v56, v53, v53
	v_pk_add_f32 v[54:55], v[54:55], v[68:69]
	v_fmac_f32_e32 v56, v52, v52
	v_fmac_f32_e32 v56, v54, v54
	v_pk_add_f32 v[48:49], v[48:49], v[70:71]
	v_fmac_f32_e32 v56, v55, v55
	v_fmac_f32_e32 v56, v48, v48
	v_pk_add_f32 v[50:51], v[50:51], v[72:73]
	v_fmac_f32_e32 v56, v49, v49
	v_fmac_f32_e32 v56, v50, v50
	v_fmac_f32_e32 v56, v51, v51
	v_add_f32_e32 v60, v61, v56
	ds_bpermute_b32 v61, v137, v60
	global_store_dwordx4 v[74:75], v[52:55], off offset:512
	global_store_dwordx4 v[74:75], v[48:51], off offset:528
	v_pk_mul_f32 v[58:59], v[80:81], v[48:49]
	v_pk_mul_f32 v[54:55], v[86:87], v[54:55]
	v_pk_mul_f32 v[52:53], v[84:85], v[52:53]
	s_waitcnt lgkmcnt(0)
	v_add_f32_e32 v48, v60, v61
	ds_bpermute_b32 v49, v136, v48
	v_pk_mul_f32 v[56:57], v[82:83], v[50:51]
	v_cvt_pk_bf16_f32 v50, v52, v53
	v_cvt_pk_bf16_f32 v51, v54, v55
	v_cvt_pk_bf16_f32 v52, v58, v59
	v_cvt_pk_bf16_f32 v53, v56, v57
	global_store_dwordx4 v[76:77], v[50:53], off offset:256
	s_and_saveexec_b64 s[26:27], s[8:9]
	s_cbranch_execz .LBB0_1151
	s_waitcnt lgkmcnt(0)
	v_add_f32_e32 v50, v48, v49
	v_lshl_add_u64 v[48:49], v[64:65], 2, s[14:15]
	global_atomic_add_f32 v[48:49], v50, off
; DI u32 pack2(float a, float b) { f32v2 v = {a, b}; return __builtin_bit_cast(u32, __builtin_convertvector(v, bf16v2)); }
;   DI void operator()(const f32x4 (&acc)[2][2][4][2], const Unit& u, int wr, int wc, int fr, int fq) const {
;     ...
;     for (int ai = 0; ai < 2; ++ai)
; #pragma unroll
;       for (int m = 0; m < 4; ++m) {
;         const int row = row0 + ai * HALF + m * 16;
;         float* dst = out + (size_t)row * DM + col0;
;         const float* src = layer == 0 ? (row < PROWS ? xp + (size_t)row * DM + col0 : xs + (size_t)(row - PROWS) * DM + col0) : dst;
;         float ss = 0.f;
; #pragma unroll
;         for (int bj = 0; bj < 2; ++bj) {
;           const f32x4 x0 = *reinterpret_cast<const f32x4*>(src + bj * HALF), x1 = *reinterpret_cast<const f32x4*>(src + bj * HALF + 4);
;           const f32x4 n0 = x0 + acc[ai][bj][m][0], n1 = x1 + acc[ai][bj][m][1];
;           *reinterpret_cast<f32x4*>(dst + bj * HALF) = n0; *reinterpret_cast<f32x4*>(dst + bj * HALF + 4) = n1;
;           ss += n0[0] * n0[0] + n0[1] * n0[1] + n0[2] * n0[2] + n0[3] * n0[3] + n1[0] * n1[0] + n1[1] * n1[1] + n1[2] * n1[2] + n1[3] * n1[3];
;           if (xw) {
;             const f32x4 h0 = n0 * wv[bj][0], h1 = n1 * wv[bj][1];
;             u32x4 pk = {pack2(h0[0], h0[1]), pack2(h0[2], h0[3]), pack2(h1[0], h1[1]), pack2(h1[2], h1[3])};
;             *reinterpret_cast<u32x4*>(xw + (size_t)row * DM + col0 + bj * HALF) = pk;
;           }
;         }
;         ss += __shfl_xor(ss, 16); ss += __shfl_xor(ss, 32);
;         if (fq == 0) atomicAdd(rs + row, ss);
;       }
.LBB0_1151:
	s_or_b64 exec, exec, s[26:27]
	v_add_u32_e32 v48, 0x90, v162
	s_waitcnt lgkmcnt(0)
	v_ashrrev_i32_e32 v49, 31, v48
	v_lshlrev_b64 v[50:51], 13, v[48:49]
	v_lshl_add_u64 v[50:51], s[44:45], 0, v[50:51]
	v_lshl_add_u64 v[58:59], v[160:161], 2, v[50:51]
	global_load_dwordx4 v[50:53], v[58:59], off
	global_load_dwordx4 v[54:57], v[58:59], off offset:16
	global_load_dwordx4 v[172:175], v[58:59], off offset:512
	global_load_dwordx4 v[176:179], v[58:59], off offset:528
	v_lshlrev_b64 v[60:61], 12, v[48:49]
	v_lshl_add_u64 v[60:61], s[52:53], 0, v[60:61]
	v_lshl_add_u64 v[60:61], v[160:161], 1, v[60:61]
	s_waitcnt vmcnt(3)
	v_pk_add_f32 v[46:47], v[46:47], v[52:53]
	v_pk_add_f32 v[44:45], v[44:45], v[50:51]
	s_waitcnt vmcnt(2)
	v_pk_add_f32 v[42:43], v[42:43], v[56:57]
	v_pk_add_f32 v[40:41], v[40:41], v[54:55]
	v_pk_mul_f32 v[52:53], v[94:95], v[46:47]
	v_pk_mul_f32 v[50:51], v[92:93], v[44:45]
	v_pk_mul_f32 v[54:55], v[90:91], v[42:43]
	v_pk_mul_f32 v[56:57], v[88:89], v[40:41]
	v_cvt_pk_bf16_f32 v50, v50, v51
	v_cvt_pk_bf16_f32 v51, v52, v53
	v_cvt_pk_bf16_f32 v52, v56, v57
	v_cvt_pk_bf16_f32 v53, v54, v55
	global_store_dwordx4 v[58:59], v[44:47], off
	global_store_dwordx4 v[58:59], v[40:43], off offset:16
	global_store_dwordx4 v[60:61], v[50:53], off
	s_waitcnt vmcnt(4)
	s_nop 1
	v_mov_b32_e32 v50, v172
	v_mov_b32_e32 v51, v173
	v_mov_b32_e32 v52, v174
	v_mov_b32_e32 v53, v175
	s_nop 0
	s_waitcnt vmcnt(3)
	v_mov_b32_e32 v54, v176
	v_mov_b32_e32 v55, v177
	v_mov_b32_e32 v56, v178
	v_mov_b32_e32 v57, v179
	v_mul_f32_e32 v45, v45, v45
	v_fmac_f32_e32 v45, v44, v44
	v_fmac_f32_e32 v45, v46, v46
	v_fmac_f32_e32 v45, v47, v47
	v_fmac_f32_e32 v45, v40, v40
	v_fmac_f32_e32 v45, v41, v41
	v_fmac_f32_e32 v45, v42, v42
	v_fmac_f32_e32 v45, v43, v43
	v_pk_add_f32 v[36:37], v[36:37], v[50:51]
	s_nop 0
	v_mul_f32_e32 v40, v37, v37
	v_pk_add_f32 v[38:39], v[38:39], v[52:53]
	v_fmac_f32_e32 v40, v36, v36
	v_fmac_f32_e32 v40, v38, v38
	v_pk_add_f32 v[32:33], v[32:33], v[54:55]
	v_fmac_f32_e32 v40, v39, v39
	v_fmac_f32_e32 v40, v32, v32
	v_pk_add_f32 v[34:35], v[34:35], v[56:57]
	v_fmac_f32_e32 v40, v33, v33
	v_fmac_f32_e32 v40, v34, v34
	v_fmac_f32_e32 v40, v35, v35
	v_add_f32_e32 v44, v45, v40
	ds_bpermute_b32 v45, v137, v44
	global_store_dwordx4 v[58:59], v[36:39], off offset:512
	global_store_dwordx4 v[58:59], v[32:35], off offset:528
	v_pk_mul_f32 v[42:43], v[80:81], v[32:33]
	v_pk_mul_f32 v[38:39], v[86:87], v[38:39]
	v_pk_mul_f32 v[36:37], v[84:85], v[36:37]
	s_waitcnt lgkmcnt(0)
	v_add_f32_e32 v32, v44, v45
	ds_bpermute_b32 v33, v136, v32
	v_pk_mul_f32 v[40:41], v[82:83], v[34:35]
	v_cvt_pk_bf16_f32 v34, v36, v37
	v_cvt_pk_bf16_f32 v35, v38, v39
	v_cvt_pk_bf16_f32 v36, v42, v43
	v_cvt_pk_bf16_f32 v37, v40, v41
	global_store_dwordx4 v[60:61], v[34:37], off offset:256
	s_and_saveexec_b64 s[26:27], s[8:9]
	s_cbranch_execz .LBB0_1153
	s_waitcnt lgkmcnt(0)
	v_add_f32_e32 v34, v32, v33
	v_lshl_add_u64 v[32:33], v[48:49], 2, s[14:15]
	global_atomic_add_f32 v[32:33], v34, off
; DI u32 pack2(float a, float b) { f32v2 v = {a, b}; return __builtin_bit_cast(u32, __builtin_convertvector(v, bf16v2)); }
;   DI void operator()(const f32x4 (&acc)[2][2][4][2], const Unit& u, int wr, int wc, int fr, int fq) const {
;     ...
;     for (int ai = 0; ai < 2; ++ai)
; #pragma unroll
;       for (int m = 0; m < 4; ++m) {
;         const int row = row0 + ai * HALF + m * 16;
;         float* dst = out + (size_t)row * DM + col0;
;         const float* src = layer == 0 ? (row < PROWS ? xp + (size_t)row * DM + col0 : xs + (size_t)(row - PROWS) * DM + col0) : dst;
;         float ss = 0.f;
; #pragma unroll
;         for (int bj = 0; bj < 2; ++bj) {
;           const f32x4 x0 = *reinterpret_cast<const f32x4*>(src + bj * HALF), x1 = *reinterpret_cast<const f32x4*>(src + bj * HALF + 4);
;           const f32x4 n0 = x0 + acc[ai][bj][m][0], n1 = x1 + acc[ai][bj][m][1];
;           *reinterpret_cast<f32x4*>(dst + bj * HALF) = n0; *reinterpret_cast<f32x4*>(dst + bj * HALF + 4) = n1;
;           ss += n0[0] * n0[0] + n0[1] * n0[1] + n0[2] * n0[2] + n0[3] * n0[3] + n1[0] * n1[0] + n1[1] * n1[1] + n1[2] * n1[2] + n1[3] * n1[3];
;           if (xw) {
;             const f32x4 h0 = n0 * wv[bj][0], h1 = n1 * wv[bj][1];
;             u32x4 pk = {pack2(h0[0], h0[1]), pack2(h0[2], h0[3]), pack2(h1[0], h1[1]), pack2(h1[2], h1[3])};
;             *reinterpret_cast<u32x4*>(xw + (size_t)row * DM + col0 + bj * HALF) = pk;
;           }
;         }
;         ss += __shfl_xor(ss, 16); ss += __shfl_xor(ss, 32);
;         if (fq == 0) atomicAdd(rs + row, ss);
;       }
.LBB0_1153:
	s_or_b64 exec, exec, s[26:27]
	v_add_u32_e32 v32, 0xa0, v162
	s_waitcnt lgkmcnt(0)
	v_ashrrev_i32_e32 v33, 31, v32
	v_lshlrev_b64 v[34:35], 13, v[32:33]
	v_lshl_add_u64 v[34:35], s[44:45], 0, v[34:35]
	v_lshl_add_u64 v[42:43], v[160:161], 2, v[34:35]
	global_load_dwordx4 v[34:37], v[42:43], off
	global_load_dwordx4 v[38:41], v[42:43], off offset:16
	global_load_dwordx4 v[172:175], v[42:43], off offset:512
	global_load_dwordx4 v[176:179], v[42:43], off offset:528
	v_lshlrev_b64 v[44:45], 12, v[32:33]
	v_lshl_add_u64 v[44:45], s[52:53], 0, v[44:45]
	v_lshl_add_u64 v[44:45], v[160:161], 1, v[44:45]
	s_waitcnt vmcnt(3)
	v_pk_add_f32 v[30:31], v[30:31], v[36:37]
	v_pk_add_f32 v[28:29], v[28:29], v[34:35]
	s_waitcnt vmcnt(2)
	v_pk_add_f32 v[26:27], v[26:27], v[40:41]
	v_pk_add_f32 v[24:25], v[24:25], v[38:39]
	v_pk_mul_f32 v[36:37], v[94:95], v[30:31]
	v_pk_mul_f32 v[34:35], v[92:93], v[28:29]
	v_pk_mul_f32 v[38:39], v[90:91], v[26:27]
	v_pk_mul_f32 v[40:41], v[88:89], v[24:25]
	v_cvt_pk_bf16_f32 v34, v34, v35
	v_cvt_pk_bf16_f32 v35, v36, v37
	v_cvt_pk_bf16_f32 v36, v40, v41
	v_cvt_pk_bf16_f32 v37, v38, v39
	global_store_dwordx4 v[42:43], v[28:31], off
	global_store_dwordx4 v[42:43], v[24:27], off offset:16
	global_store_dwordx4 v[44:45], v[34:37], off
	s_waitcnt vmcnt(4)
	s_nop 1
	v_mov_b32_e32 v34, v172
	v_mov_b32_e32 v35, v173
	v_mov_b32_e32 v36, v174
	v_mov_b32_e32 v37, v175
	s_nop 0
	s_waitcnt vmcnt(3)
	v_mov_b32_e32 v38, v176
	v_mov_b32_e32 v39, v177
	v_mov_b32_e32 v40, v178
	v_mov_b32_e32 v41, v179
	v_mul_f32_e32 v29, v29, v29
	v_fmac_f32_e32 v29, v28, v28
	v_fmac_f32_e32 v29, v30, v30
	v_fmac_f32_e32 v29, v31, v31
	v_fmac_f32_e32 v29, v24, v24
	v_fmac_f32_e32 v29, v25, v25
	v_fmac_f32_e32 v29, v26, v26
	v_fmac_f32_e32 v29, v27, v27
	v_pk_add_f32 v[20:21], v[20:21], v[34:35]
	s_nop 0
	v_mul_f32_e32 v24, v21, v21
	v_pk_add_f32 v[22:23], v[22:23], v[36:37]
	v_fmac_f32_e32 v24, v20, v20
	v_fmac_f32_e32 v24, v22, v22
	v_pk_add_f32 v[16:17], v[16:17], v[38:39]
	v_fmac_f32_e32 v24, v23, v23
	v_fmac_f32_e32 v24, v16, v16
	v_pk_add_f32 v[18:19], v[18:19], v[40:41]
	v_fmac_f32_e32 v24, v17, v17
	v_fmac_f32_e32 v24, v18, v18
	v_fmac_f32_e32 v24, v19, v19
	v_add_f32_e32 v28, v29, v24
	ds_bpermute_b32 v29, v137, v28
	global_store_dwordx4 v[42:43], v[20:23], off offset:512
	global_store_dwordx4 v[42:43], v[16:19], off offset:528
	v_pk_mul_f32 v[26:27], v[80:81], v[16:17]
	v_pk_mul_f32 v[22:23], v[86:87], v[22:23]
	v_pk_mul_f32 v[20:21], v[84:85], v[20:21]
	s_waitcnt lgkmcnt(0)
	v_add_f32_e32 v16, v28, v29
	ds_bpermute_b32 v17, v136, v16
	v_pk_mul_f32 v[24:25], v[82:83], v[18:19]
	v_cvt_pk_bf16_f32 v18, v20, v21
	v_cvt_pk_bf16_f32 v19, v22, v23
	v_cvt_pk_bf16_f32 v20, v26, v27
	v_cvt_pk_bf16_f32 v21, v24, v25
	global_store_dwordx4 v[44:45], v[18:21], off offset:256
	s_and_saveexec_b64 s[26:27], s[8:9]
	s_cbranch_execz .LBB0_1155
	s_waitcnt lgkmcnt(0)
	v_add_f32_e32 v18, v16, v17
	v_lshl_add_u64 v[16:17], v[32:33], 2, s[14:15]
	global_atomic_add_f32 v[16:17], v18, off
.LBB0_1155:
	s_or_b64 exec, exec, s[26:27]
	v_add_u32_e32 v16, 0xb0, v162
	s_waitcnt lgkmcnt(0)
	v_ashrrev_i32_e32 v17, 31, v16
	v_lshlrev_b64 v[18:19], 13, v[16:17]
	v_lshl_add_u64 v[18:19], s[44:45], 0, v[18:19]
	v_lshl_add_u64 v[26:27], v[160:161], 2, v[18:19]
	global_load_dwordx4 v[18:21], v[26:27], off
	global_load_dwordx4 v[22:25], v[26:27], off offset:16
	global_load_dwordx4 v[172:175], v[26:27], off offset:512
	global_load_dwordx4 v[176:179], v[26:27], off offset:528
	v_lshlrev_b64 v[28:29], 12, v[16:17]
	v_lshl_add_u64 v[28:29], s[52:53], 0, v[28:29]
	v_lshl_add_u64 v[28:29], v[160:161], 1, v[28:29]
	s_waitcnt vmcnt(3)
	v_pk_add_f32 v[14:15], v[14:15], v[20:21]
	v_pk_add_f32 v[12:13], v[12:13], v[18:19]
	s_waitcnt vmcnt(2)
	v_pk_add_f32 v[10:11], v[10:11], v[24:25]
	v_pk_add_f32 v[8:9], v[8:9], v[22:23]
	v_pk_mul_f32 v[20:21], v[94:95], v[14:15]
	v_pk_mul_f32 v[18:19], v[92:93], v[12:13]
	v_pk_mul_f32 v[22:23], v[90:91], v[10:11]
	v_pk_mul_f32 v[24:25], v[88:89], v[8:9]
	v_cvt_pk_bf16_f32 v18, v18, v19
	v_cvt_pk_bf16_f32 v19, v20, v21
	v_cvt_pk_bf16_f32 v20, v24, v25
	v_cvt_pk_bf16_f32 v21, v22, v23
	global_store_dwordx4 v[26:27], v[12:15], off
	global_store_dwordx4 v[26:27], v[8:11], off offset:16
	global_store_dwordx4 v[28:29], v[18:21], off
	s_waitcnt vmcnt(4)
	s_nop 1
	v_mov_b32_e32 v18, v172
	v_mov_b32_e32 v19, v173
	v_mov_b32_e32 v20, v174
	v_mov_b32_e32 v21, v175
	s_nop 0
	s_waitcnt vmcnt(3)
	v_mov_b32_e32 v22, v176
	v_mov_b32_e32 v23, v177
	v_mov_b32_e32 v24, v178
	v_mov_b32_e32 v25, v179
	v_mul_f32_e32 v13, v13, v13
	v_fmac_f32_e32 v13, v12, v12
	v_fmac_f32_e32 v13, v14, v14
	v_fmac_f32_e32 v13, v15, v15
	v_fmac_f32_e32 v13, v8, v8
	v_fmac_f32_e32 v13, v9, v9
	v_fmac_f32_e32 v13, v10, v10
	v_fmac_f32_e32 v13, v11, v11
	v_pk_add_f32 v[4:5], v[4:5], v[18:19]
	s_nop 0
	v_mul_f32_e32 v8, v5, v5
	v_pk_add_f32 v[6:7], v[6:7], v[20:21]
	v_fmac_f32_e32 v8, v4, v4
	v_fmac_f32_e32 v8, v6, v6
	v_pk_add_f32 v[0:1], v[0:1], v[22:23]
	v_fmac_f32_e32 v8, v7, v7
	v_fmac_f32_e32 v8, v0, v0
	v_pk_add_f32 v[2:3], v[2:3], v[24:25]
	v_fmac_f32_e32 v8, v1, v1
	v_fmac_f32_e32 v8, v2, v2
	v_fmac_f32_e32 v8, v3, v3
	v_add_f32_e32 v12, v13, v8
	ds_bpermute_b32 v13, v137, v12
	global_store_dwordx4 v[26:27], v[4:7], off offset:512
	global_store_dwordx4 v[26:27], v[0:3], off offset:528
	v_pk_mul_f32 v[10:11], v[80:81], v[0:1]
	v_pk_mul_f32 v[6:7], v[86:87], v[6:7]
	v_pk_mul_f32 v[4:5], v[84:85], v[4:5]
	s_waitcnt lgkmcnt(0)
	v_add_f32_e32 v0, v12, v13
	ds_bpermute_b32 v1, v136, v0
	v_pk_mul_f32 v[8:9], v[82:83], v[2:3]
	v_cvt_pk_bf16_f32 v2, v4, v5
	v_cvt_pk_bf16_f32 v3, v6, v7
	v_cvt_pk_bf16_f32 v4, v10, v11
	v_cvt_pk_bf16_f32 v5, v8, v9
	global_store_dwordx4 v[28:29], v[2:5], off offset:256
	s_and_saveexec_b64 s[26:27], s[8:9]
	s_cbranch_execz .LBB0_1136
	s_waitcnt lgkmcnt(0)
	v_add_f32_e32 v2, v0, v1
	v_lshl_add_u64 v[0:1], v[16:17], 2, s[14:15]
	global_atomic_add_f32 v[0:1], v2, off
	s_branch .LBB0_1136
